# k2=2 DMA rebalance plus the closing s_barrier of every MFMA segment moved before its last MFMA
# baseline (speedup 1.0000x reference)
.LBB0_166:
	ds_read_b128 v[128:131], v189
	ds_read_b128 v[132:135], v189 offset:1024
	ds_read_b128 v[136:139], v189 offset:2048
	ds_read_b128 v[140:143], v189 offset:3072
	ds_read_b128 v[166:169], v189 offset:16384
	ds_read_b128 v[170:173], v189 offset:17408
	ds_read_b128 v[174:177], v189 offset:18432
	ds_read_b128 v[192:195], v189 offset:19456
	s_add_u32 s23, s26, 0xfffc0080
	s_addc_u32 s28, s27, -1
	s_cmp_eq_u32 s53, 12
	s_cselect_b32 s31, s7, s28
	s_cselect_b32 s30, s19, s23
	s_cselect_b32 s29, s17, s52
	s_cselect_b32 s28, s50, s51
	s_add_i32 m0, s15, 0xc000
	ds_read_b128 v[196:199], v190
	ds_read_b128 v[200:203], v190 offset:1024
	ds_read_b128 v[204:207], v190 offset:2048
	ds_read_b128 v[208:211], v190 offset:3072
	ds_read_b128 v[212:215], v190 offset:4096
	ds_read_b128 v[216:219], v190 offset:5120
	ds_read_b128 v[220:223], v190 offset:6144
	ds_read_b128 v[224:227], v190 offset:7168
	global_load_lds_dwordx4 v144, s[26:27]
	s_add_i32 m0, s15, 0xe000
	v_mov_b32_e32 v149, v145
	global_load_lds_dwordx4 v148, s[26:27]
	s_waitcnt vmcnt(8)
	s_waitcnt lgkmcnt(0)
	s_barrier
	s_setprio 1
	s_waitcnt lgkmcnt(0)
	v_mfma_f32_16x16x32_bf16 v[124:127], v[128:131], v[196:199], v[124:127]
	v_mfma_f32_16x16x32_bf16 v[120:123], v[136:139], v[196:199], v[120:123]
	v_mfma_f32_16x16x32_bf16 v[116:119], v[128:131], v[204:207], v[116:119]
	v_mfma_f32_16x16x32_bf16 v[112:115], v[136:139], v[204:207], v[112:115]
	v_mfma_f32_16x16x32_bf16 v[100:103], v[128:131], v[212:215], v[100:103]
	v_mfma_f32_16x16x32_bf16 v[96:99], v[136:139], v[212:215], v[96:99]
	v_mfma_f32_16x16x32_bf16 v[84:87], v[128:131], v[220:223], v[84:87]
	v_mfma_f32_16x16x32_bf16 v[80:83], v[136:139], v[220:223], v[80:83]
	v_mfma_f32_16x16x32_bf16 v[124:127], v[132:135], v[200:203], v[124:127]
	v_mfma_f32_16x16x32_bf16 v[120:123], v[140:143], v[200:203], v[120:123]
	v_mfma_f32_16x16x32_bf16 v[116:119], v[132:135], v[208:211], v[116:119]
	v_mfma_f32_16x16x32_bf16 v[112:115], v[140:143], v[208:211], v[112:115]
	v_mfma_f32_16x16x32_bf16 v[100:103], v[132:135], v[216:219], v[100:103]
	v_mfma_f32_16x16x32_bf16 v[96:99], v[140:143], v[216:219], v[96:99]
	v_mfma_f32_16x16x32_bf16 v[84:87], v[132:135], v[224:227], v[84:87]
	v_mfma_f32_16x16x32_bf16 v[80:83], v[140:143], v[224:227], v[80:83]
	s_setprio 0
	s_setprio 1
	v_mfma_f32_16x16x32_bf16 v[108:111], v[166:169], v[196:199], v[108:111]
	v_mfma_f32_16x16x32_bf16 v[104:107], v[174:177], v[196:199], v[104:107]
	v_mfma_f32_16x16x32_bf16 v[92:95], v[166:169], v[204:207], v[92:95]
	v_mfma_f32_16x16x32_bf16 v[88:91], v[174:177], v[204:207], v[88:91]
	v_mfma_f32_16x16x32_bf16 v[76:79], v[166:169], v[212:215], v[76:79]
	v_mfma_f32_16x16x32_bf16 v[72:75], v[174:177], v[212:215], v[72:75]
	v_mfma_f32_16x16x32_bf16 v[68:71], v[166:169], v[220:223], v[68:71]
	v_mfma_f32_16x16x32_bf16 v[64:67], v[174:177], v[220:223], v[64:67]
	v_mfma_f32_16x16x32_bf16 v[108:111], v[170:173], v[200:203], v[108:111]
	v_mfma_f32_16x16x32_bf16 v[104:107], v[192:195], v[200:203], v[104:107]
	v_mfma_f32_16x16x32_bf16 v[92:95], v[170:173], v[208:211], v[92:95]
	v_mfma_f32_16x16x32_bf16 v[88:91], v[192:195], v[208:211], v[88:91]
	v_mfma_f32_16x16x32_bf16 v[76:79], v[170:173], v[216:219], v[76:79]
	v_mfma_f32_16x16x32_bf16 v[72:75], v[192:195], v[216:219], v[72:75]
	v_mfma_f32_16x16x32_bf16 v[68:71], v[170:173], v[224:227], v[68:71]
	s_barrier
	v_mfma_f32_16x16x32_bf16 v[64:67], v[192:195], v[224:227], v[64:67]
	s_setprio 0
	s_mov_b32 m0, s34
	ds_read_b128 v[196:199], v190 offset:16384
	ds_read_b128 v[200:203], v190 offset:17408
	ds_read_b128 v[204:207], v190 offset:18432
	ds_read_b128 v[208:211], v190 offset:19456
	ds_read_b128 v[212:215], v190 offset:20480
	ds_read_b128 v[216:219], v190 offset:21504
	ds_read_b128 v[220:223], v190 offset:22528
	ds_read_b128 v[224:227], v190 offset:23552
	global_load_lds_dwordx4 v146, s[28:29]
	s_mov_b32 m0, s35
	s_add_u32 s54, s28, 0x40000
	global_load_lds_dwordx4 v150, s[28:29]
	s_addc_u32 s55, s29, 0
	s_mov_b32 m0, s36
	v_mov_b32_e32 v147, v145
	global_load_lds_dwordx4 v146, s[54:55]
	s_mov_b32 m0, s37
	v_mov_b32_e32 v151, v145
	global_load_lds_dwordx4 v150, s[54:55]
	s_waitcnt vmcnt(6)
	s_waitcnt lgkmcnt(0)
	s_barrier
	s_setprio 1
	s_waitcnt lgkmcnt(0)
	v_mfma_f32_16x16x32_bf16 v[60:63], v[128:131], v[196:199], v[60:63]
	v_mfma_f32_16x16x32_bf16 v[56:59], v[136:139], v[196:199], v[56:59]
	s_mov_b32 m0, s15
	v_lshl_add_u64 v[180:181], s[28:29], 0, v[146:147]
	v_mfma_f32_16x16x32_bf16 v[52:55], v[128:131], v[204:207], v[52:55]
	global_load_lds_dwordx4 v144, s[30:31]
	v_mfma_f32_16x16x32_bf16 v[48:51], v[136:139], v[204:207], v[48:51]
	v_mfma_f32_16x16x32_bf16 v[36:39], v[128:131], v[212:215], v[36:39]
	v_mfma_f32_16x16x32_bf16 v[32:35], v[136:139], v[212:215], v[32:35]
	v_mfma_f32_16x16x32_bf16 v[20:23], v[128:131], v[220:223], v[20:23]
	v_mfma_f32_16x16x32_bf16 v[16:19], v[136:139], v[220:223], v[16:19]
	v_mfma_f32_16x16x32_bf16 v[60:63], v[132:135], v[200:203], v[60:63]
	v_mfma_f32_16x16x32_bf16 v[56:59], v[140:143], v[200:203], v[56:59]
	v_mfma_f32_16x16x32_bf16 v[52:55], v[132:135], v[208:211], v[52:55]
	v_mfma_f32_16x16x32_bf16 v[48:51], v[140:143], v[208:211], v[48:51]
	v_mfma_f32_16x16x32_bf16 v[36:39], v[132:135], v[216:219], v[36:39]
	v_mfma_f32_16x16x32_bf16 v[32:35], v[140:143], v[216:219], v[32:35]
	v_mfma_f32_16x16x32_bf16 v[20:23], v[132:135], v[224:227], v[20:23]
	v_mfma_f32_16x16x32_bf16 v[16:19], v[140:143], v[224:227], v[16:19]
	s_mov_b32 m0, s38
	v_lshl_add_u64 v[228:229], s[28:29], 0, v[150:151]
	s_setprio 0
	s_setprio 1
	v_mfma_f32_16x16x32_bf16 v[44:47], v[166:169], v[196:199], v[44:47]
	global_load_lds_dwordx4 v148, s[30:31]
	v_lshl_add_u64 v[230:231], s[30:31], 0, v[144:145]
	v_lshl_add_u64 v[232:233], s[30:31], 0, v[148:149]
	v_mfma_f32_16x16x32_bf16 v[40:43], v[174:177], v[196:199], v[40:43]
	v_mfma_f32_16x16x32_bf16 v[28:31], v[166:169], v[204:207], v[28:31]
	v_mfma_f32_16x16x32_bf16 v[24:27], v[174:177], v[204:207], v[24:27]
	v_mfma_f32_16x16x32_bf16 v[12:15], v[166:169], v[212:215], v[12:15]
	v_mfma_f32_16x16x32_bf16 v[8:11], v[174:177], v[212:215], v[8:11]
	v_mfma_f32_16x16x32_bf16 v[4:7], v[166:169], v[220:223], v[4:7]
	v_mfma_f32_16x16x32_bf16 v[0:3], v[174:177], v[220:223], v[0:3]
	v_mfma_f32_16x16x32_bf16 v[44:47], v[170:173], v[200:203], v[44:47]
	v_mfma_f32_16x16x32_bf16 v[40:43], v[192:195], v[200:203], v[40:43]
	v_mfma_f32_16x16x32_bf16 v[28:31], v[170:173], v[208:211], v[28:31]
	v_mfma_f32_16x16x32_bf16 v[24:27], v[192:195], v[208:211], v[24:27]
	v_mfma_f32_16x16x32_bf16 v[12:15], v[170:173], v[216:219], v[12:15]
	v_mfma_f32_16x16x32_bf16 v[8:11], v[192:195], v[216:219], v[8:11]
	v_mfma_f32_16x16x32_bf16 v[4:7], v[170:173], v[224:227], v[4:7]
	s_barrier
	v_mfma_f32_16x16x32_bf16 v[0:3], v[192:195], v[224:227], v[0:3]
	s_setprio 0
	ds_read_b128 v[128:131], v189 offset:32768
	ds_read_b128 v[132:135], v189 offset:33792
	ds_read_b128 v[136:139], v189 offset:34816
	ds_read_b128 v[140:143], v189 offset:35840
	ds_read_b128 v[166:169], v189 offset:49152
	ds_read_b128 v[170:173], v189 offset:50176
	ds_read_b128 v[174:177], v189 offset:51200
	ds_read_b128 v[192:195], v189 offset:52224
	s_add_u32 s30, s30, 0x40000
	s_addc_u32 s31, s31, 0
	s_mov_b32 m0, s39
	ds_read_b128 v[196:199], v190 offset:32768
	ds_read_b128 v[200:203], v190 offset:33792
	ds_read_b128 v[204:207], v190 offset:34816
	ds_read_b128 v[208:211], v190 offset:35840
	ds_read_b128 v[212:215], v190 offset:36864
	ds_read_b128 v[216:219], v190 offset:37888
	ds_read_b128 v[220:223], v190 offset:38912
	ds_read_b128 v[224:227], v190 offset:39936
	global_load_lds_dwordx4 v144, s[30:31]
	s_mov_b32 m0, s40
	s_nop 0
	global_load_lds_dwordx4 v148, s[30:31]
	s_waitcnt vmcnt(8)
	s_waitcnt lgkmcnt(0)
	s_barrier
	s_setprio 1
	s_waitcnt lgkmcnt(0)
	v_mfma_f32_16x16x32_bf16 v[124:127], v[128:131], v[196:199], v[124:127]
	v_mfma_f32_16x16x32_bf16 v[120:123], v[136:139], v[196:199], v[120:123]
	v_mfma_f32_16x16x32_bf16 v[116:119], v[128:131], v[204:207], v[116:119]
	v_mfma_f32_16x16x32_bf16 v[112:115], v[136:139], v[204:207], v[112:115]
	v_mfma_f32_16x16x32_bf16 v[100:103], v[128:131], v[212:215], v[100:103]
	v_mfma_f32_16x16x32_bf16 v[96:99], v[136:139], v[212:215], v[96:99]
	v_mfma_f32_16x16x32_bf16 v[84:87], v[128:131], v[220:223], v[84:87]
	v_mfma_f32_16x16x32_bf16 v[80:83], v[136:139], v[220:223], v[80:83]
	v_mfma_f32_16x16x32_bf16 v[124:127], v[132:135], v[200:203], v[124:127]
	v_mfma_f32_16x16x32_bf16 v[120:123], v[140:143], v[200:203], v[120:123]
	v_mfma_f32_16x16x32_bf16 v[116:119], v[132:135], v[208:211], v[116:119]
	v_mfma_f32_16x16x32_bf16 v[112:115], v[140:143], v[208:211], v[112:115]
	v_mfma_f32_16x16x32_bf16 v[100:103], v[132:135], v[216:219], v[100:103]
	v_mfma_f32_16x16x32_bf16 v[96:99], v[140:143], v[216:219], v[96:99]
	v_mfma_f32_16x16x32_bf16 v[84:87], v[132:135], v[224:227], v[84:87]
	v_mfma_f32_16x16x32_bf16 v[80:83], v[140:143], v[224:227], v[80:83]
	s_setprio 0
	s_setprio 1
	v_mfma_f32_16x16x32_bf16 v[108:111], v[166:169], v[196:199], v[108:111]
	v_mfma_f32_16x16x32_bf16 v[104:107], v[174:177], v[196:199], v[104:107]
	v_mfma_f32_16x16x32_bf16 v[92:95], v[166:169], v[204:207], v[92:95]
	v_mfma_f32_16x16x32_bf16 v[88:91], v[174:177], v[204:207], v[88:91]
	v_mfma_f32_16x16x32_bf16 v[76:79], v[166:169], v[212:215], v[76:79]
	v_mfma_f32_16x16x32_bf16 v[72:75], v[174:177], v[212:215], v[72:75]
	v_mfma_f32_16x16x32_bf16 v[68:71], v[166:169], v[220:223], v[68:71]
	v_mfma_f32_16x16x32_bf16 v[64:67], v[174:177], v[220:223], v[64:67]
	v_mfma_f32_16x16x32_bf16 v[108:111], v[170:173], v[200:203], v[108:111]
	v_mfma_f32_16x16x32_bf16 v[104:107], v[192:195], v[200:203], v[104:107]
	v_mfma_f32_16x16x32_bf16 v[92:95], v[170:173], v[208:211], v[92:95]
	v_mfma_f32_16x16x32_bf16 v[88:91], v[192:195], v[208:211], v[88:91]
	v_mfma_f32_16x16x32_bf16 v[76:79], v[170:173], v[216:219], v[76:79]
	v_mfma_f32_16x16x32_bf16 v[72:75], v[192:195], v[216:219], v[72:75]
	v_mfma_f32_16x16x32_bf16 v[68:71], v[170:173], v[224:227], v[68:71]
	s_barrier
	v_mfma_f32_16x16x32_bf16 v[64:67], v[192:195], v[224:227], v[64:67]
	s_setprio 0
	s_mov_b32 m0, s42
	v_lshl_add_u64 v[180:181], v[180:181], 0, s[10:11]
	ds_read_b128 v[196:199], v190 offset:49152
	ds_read_b128 v[200:203], v190 offset:50176
	ds_read_b128 v[204:207], v190 offset:51200
	ds_read_b128 v[208:211], v190 offset:52224
	ds_read_b128 v[212:215], v190 offset:53248
	ds_read_b128 v[216:219], v190 offset:54272
	ds_read_b128 v[220:223], v190 offset:55296
	ds_read_b128 v[224:227], v190 offset:56320
	global_load_lds_dwordx4 v[180:181], off
	v_lshl_add_u64 v[180:181], v[228:229], 0, s[10:11]
	s_mov_b32 m0, s43
	s_add_u32 s28, s28, 0x40080
	global_load_lds_dwordx4 v[180:181], off
	s_addc_u32 s29, s29, 0
	s_mov_b32 m0, s48
	v_lshl_add_u64 v[180:181], v[230:231], 0, s[10:11]
	global_load_lds_dwordx4 v146, s[28:29]
	s_mov_b32 m0, s49
	s_nop 0
	global_load_lds_dwordx4 v150, s[28:29]
	s_waitcnt vmcnt(6)
	s_waitcnt lgkmcnt(0)
	s_barrier
	s_setprio 1
	s_waitcnt lgkmcnt(0)
	v_mfma_f32_16x16x32_bf16 v[60:63], v[128:131], v[196:199], v[60:63]
	v_mfma_f32_16x16x32_bf16 v[56:59], v[136:139], v[196:199], v[56:59]
	s_mov_b32 m0, s44
	v_mfma_f32_16x16x32_bf16 v[52:55], v[128:131], v[204:207], v[52:55]
	global_load_lds_dwordx4 v[180:181], off
	v_mfma_f32_16x16x32_bf16 v[48:51], v[136:139], v[204:207], v[48:51]
	v_mfma_f32_16x16x32_bf16 v[36:39], v[128:131], v[212:215], v[36:39]
	v_mfma_f32_16x16x32_bf16 v[32:35], v[136:139], v[212:215], v[32:35]
	v_mfma_f32_16x16x32_bf16 v[20:23], v[128:131], v[220:223], v[20:23]
	v_mfma_f32_16x16x32_bf16 v[16:19], v[136:139], v[220:223], v[16:19]
	v_mfma_f32_16x16x32_bf16 v[60:63], v[132:135], v[200:203], v[60:63]
	v_mfma_f32_16x16x32_bf16 v[56:59], v[140:143], v[200:203], v[56:59]
	v_mfma_f32_16x16x32_bf16 v[52:55], v[132:135], v[208:211], v[52:55]
	v_mfma_f32_16x16x32_bf16 v[48:51], v[140:143], v[208:211], v[48:51]
	v_mfma_f32_16x16x32_bf16 v[36:39], v[132:135], v[216:219], v[36:39]
	v_mfma_f32_16x16x32_bf16 v[32:35], v[140:143], v[216:219], v[32:35]
	v_mfma_f32_16x16x32_bf16 v[20:23], v[132:135], v[224:227], v[20:23]
	v_mfma_f32_16x16x32_bf16 v[16:19], v[140:143], v[224:227], v[16:19]
	v_lshl_add_u64 v[180:181], v[232:233], 0, s[10:11]
	s_mov_b32 m0, s45
	s_setprio 0
	s_setprio 1
	v_mfma_f32_16x16x32_bf16 v[44:47], v[166:169], v[196:199], v[44:47]
	global_load_lds_dwordx4 v[180:181], off
	v_mfma_f32_16x16x32_bf16 v[40:43], v[174:177], v[196:199], v[40:43]
	v_mfma_f32_16x16x32_bf16 v[28:31], v[166:169], v[204:207], v[28:31]
	v_mfma_f32_16x16x32_bf16 v[24:27], v[174:177], v[204:207], v[24:27]
	v_mfma_f32_16x16x32_bf16 v[12:15], v[166:169], v[212:215], v[12:15]
	v_mfma_f32_16x16x32_bf16 v[8:11], v[174:177], v[212:215], v[8:11]
	v_mfma_f32_16x16x32_bf16 v[4:7], v[166:169], v[220:223], v[4:7]
	v_mfma_f32_16x16x32_bf16 v[0:3], v[174:177], v[220:223], v[0:3]
	v_mfma_f32_16x16x32_bf16 v[44:47], v[170:173], v[200:203], v[44:47]
	v_mfma_f32_16x16x32_bf16 v[40:43], v[192:195], v[200:203], v[40:43]
	v_mfma_f32_16x16x32_bf16 v[28:31], v[170:173], v[208:211], v[28:31]
	v_mfma_f32_16x16x32_bf16 v[24:27], v[192:195], v[208:211], v[24:27]
	v_mfma_f32_16x16x32_bf16 v[12:15], v[170:173], v[216:219], v[12:15]
	v_mfma_f32_16x16x32_bf16 v[8:11], v[192:195], v[216:219], v[8:11]
	v_mfma_f32_16x16x32_bf16 v[4:7], v[170:173], v[224:227], v[4:7]
	s_barrier
	v_mfma_f32_16x16x32_bf16 v[0:3], v[192:195], v[224:227], v[0:3]
	s_nop 0
	s_setprio 0
	s_add_i32 s53, s53, 2
	s_add_u32 s26, s26, 0x100
	s_addc_u32 s27, s27, 0
	s_add_u32 s51, s51, 0x100
	s_addc_u32 s52, s52, 0
	s_cmp_gt_u32 s53, 13
	s_cbranch_scc0 .LBB0_166
	s_and_b64 vcc, exec, s[12:13]
	s_cbranch_vccz .LBB0_169
	s_barrier

.LBB0_206:
	ds_read_b128 v[144:147], v142
	ds_read_b128 v[148:151], v142 offset:1024
	ds_read_b128 v[152:155], v142 offset:2048
	ds_read_b128 v[156:159], v142 offset:3072
	ds_read_b128 v[164:167], v142 offset:16384
	ds_read_b128 v[168:171], v142 offset:17408
	ds_read_b128 v[172:175], v142 offset:18432
	ds_read_b128 v[176:179], v142 offset:19456
	s_add_u32 s23, s26, 0xfffc0080
	s_addc_u32 s28, s27, -1
	s_cmp_eq_u32 s53, 12
	s_cselect_b32 s31, s15, s28
	s_cselect_b32 s30, s49, s23
	s_cselect_b32 s29, s13, s52
	s_cselect_b32 s28, s50, s51
	s_add_i32 m0, s3, 0xc000
	ds_read_b128 v[180:183], v143
	ds_read_b128 v[186:189], v143 offset:1024
	ds_read_b128 v[190:193], v143 offset:2048
	ds_read_b128 v[194:197], v143 offset:3072
	ds_read_b128 v[198:201], v143 offset:4096
	ds_read_b128 v[202:205], v143 offset:5120
	ds_read_b128 v[206:209], v143 offset:6144
	ds_read_b128 v[210:213], v143 offset:7168
	global_load_lds_dwordx4 v128, s[26:27]
	s_add_i32 m0, s3, 0xe000
	v_mov_b32_e32 v131, v129
	global_load_lds_dwordx4 v130, s[26:27]
	s_waitcnt vmcnt(8)
	s_waitcnt lgkmcnt(0)
	s_barrier
	s_setprio 1
	s_waitcnt lgkmcnt(0)
	v_mfma_f32_16x16x32_bf16 v[124:127], v[144:147], v[180:183], v[124:127]
	v_mfma_f32_16x16x32_bf16 v[120:123], v[152:155], v[180:183], v[120:123]
	v_mfma_f32_16x16x32_bf16 v[116:119], v[144:147], v[190:193], v[116:119]
	v_mfma_f32_16x16x32_bf16 v[112:115], v[152:155], v[190:193], v[112:115]
	v_mfma_f32_16x16x32_bf16 v[100:103], v[144:147], v[198:201], v[100:103]
	v_mfma_f32_16x16x32_bf16 v[96:99], v[152:155], v[198:201], v[96:99]
	v_mfma_f32_16x16x32_bf16 v[84:87], v[144:147], v[206:209], v[84:87]
	v_mfma_f32_16x16x32_bf16 v[80:83], v[152:155], v[206:209], v[80:83]
	v_mfma_f32_16x16x32_bf16 v[124:127], v[148:151], v[186:189], v[124:127]
	v_mfma_f32_16x16x32_bf16 v[120:123], v[156:159], v[186:189], v[120:123]
	v_mfma_f32_16x16x32_bf16 v[116:119], v[148:151], v[194:197], v[116:119]
	v_mfma_f32_16x16x32_bf16 v[112:115], v[156:159], v[194:197], v[112:115]
	v_mfma_f32_16x16x32_bf16 v[100:103], v[148:151], v[202:205], v[100:103]
	v_mfma_f32_16x16x32_bf16 v[96:99], v[156:159], v[202:205], v[96:99]
	v_mfma_f32_16x16x32_bf16 v[84:87], v[148:151], v[210:213], v[84:87]
	v_mfma_f32_16x16x32_bf16 v[80:83], v[156:159], v[210:213], v[80:83]
	s_setprio 0
	s_setprio 1
	v_mfma_f32_16x16x32_bf16 v[108:111], v[164:167], v[180:183], v[108:111]
	v_mfma_f32_16x16x32_bf16 v[104:107], v[172:175], v[180:183], v[104:107]
	v_mfma_f32_16x16x32_bf16 v[92:95], v[164:167], v[190:193], v[92:95]
	v_mfma_f32_16x16x32_bf16 v[88:91], v[172:175], v[190:193], v[88:91]
	v_mfma_f32_16x16x32_bf16 v[76:79], v[164:167], v[198:201], v[76:79]
	v_mfma_f32_16x16x32_bf16 v[72:75], v[172:175], v[198:201], v[72:75]
	v_mfma_f32_16x16x32_bf16 v[68:71], v[164:167], v[206:209], v[68:71]
	v_mfma_f32_16x16x32_bf16 v[64:67], v[172:175], v[206:209], v[64:67]
	v_mfma_f32_16x16x32_bf16 v[108:111], v[168:171], v[186:189], v[108:111]
	v_mfma_f32_16x16x32_bf16 v[104:107], v[176:179], v[186:189], v[104:107]
	v_mfma_f32_16x16x32_bf16 v[92:95], v[168:171], v[194:197], v[92:95]
	v_mfma_f32_16x16x32_bf16 v[88:91], v[176:179], v[194:197], v[88:91]
	v_mfma_f32_16x16x32_bf16 v[76:79], v[168:171], v[202:205], v[76:79]
	v_mfma_f32_16x16x32_bf16 v[72:75], v[176:179], v[202:205], v[72:75]
	v_mfma_f32_16x16x32_bf16 v[68:71], v[168:171], v[210:213], v[68:71]
	s_barrier
	v_mfma_f32_16x16x32_bf16 v[64:67], v[176:179], v[210:213], v[64:67]
	s_setprio 0
	s_mov_b32 m0, s17
	ds_read_b128 v[180:183], v143 offset:16384
	ds_read_b128 v[186:189], v143 offset:17408
	ds_read_b128 v[190:193], v143 offset:18432
	ds_read_b128 v[194:197], v143 offset:19456
	ds_read_b128 v[198:201], v143 offset:20480
	ds_read_b128 v[202:205], v143 offset:21504
	ds_read_b128 v[206:209], v143 offset:22528
	ds_read_b128 v[210:213], v143 offset:23552
	global_load_lds_dwordx4 v138, s[28:29]
	s_mov_b32 m0, s22
	s_add_u32 s54, s28, 0x40000
	global_load_lds_dwordx4 v132, s[28:29]
	s_addc_u32 s55, s29, 0
	s_mov_b32 m0, s34
	v_mov_b32_e32 v139, v129
	global_load_lds_dwordx4 v138, s[54:55]
	s_mov_b32 m0, s35
	v_mov_b32_e32 v133, v129
	global_load_lds_dwordx4 v132, s[54:55]
	s_waitcnt vmcnt(6)
	s_waitcnt lgkmcnt(0)
	s_barrier
	s_setprio 1
	s_waitcnt lgkmcnt(0)
	v_mfma_f32_16x16x32_bf16 v[60:63], v[144:147], v[180:183], v[60:63]
	v_mfma_f32_16x16x32_bf16 v[56:59], v[152:155], v[180:183], v[56:59]
	s_mov_b32 m0, s3
	v_lshl_add_u64 v[214:215], s[28:29], 0, v[138:139]
	v_mfma_f32_16x16x32_bf16 v[52:55], v[144:147], v[190:193], v[52:55]
	global_load_lds_dwordx4 v128, s[30:31]
	v_mfma_f32_16x16x32_bf16 v[48:51], v[152:155], v[190:193], v[48:51]
	v_mfma_f32_16x16x32_bf16 v[36:39], v[144:147], v[198:201], v[36:39]
	v_mfma_f32_16x16x32_bf16 v[32:35], v[152:155], v[198:201], v[32:35]
	v_mfma_f32_16x16x32_bf16 v[20:23], v[144:147], v[206:209], v[20:23]
	v_mfma_f32_16x16x32_bf16 v[16:19], v[152:155], v[206:209], v[16:19]
	v_mfma_f32_16x16x32_bf16 v[60:63], v[148:151], v[186:189], v[60:63]
	v_mfma_f32_16x16x32_bf16 v[56:59], v[156:159], v[186:189], v[56:59]
	v_mfma_f32_16x16x32_bf16 v[52:55], v[148:151], v[194:197], v[52:55]
	v_mfma_f32_16x16x32_bf16 v[48:51], v[156:159], v[194:197], v[48:51]
	v_mfma_f32_16x16x32_bf16 v[36:39], v[148:151], v[202:205], v[36:39]
	v_mfma_f32_16x16x32_bf16 v[32:35], v[156:159], v[202:205], v[32:35]
	v_mfma_f32_16x16x32_bf16 v[20:23], v[148:151], v[210:213], v[20:23]
	v_mfma_f32_16x16x32_bf16 v[16:19], v[156:159], v[210:213], v[16:19]
	s_mov_b32 m0, s36
	v_lshl_add_u64 v[216:217], s[28:29], 0, v[132:133]
	s_setprio 0
	s_setprio 1
	v_mfma_f32_16x16x32_bf16 v[44:47], v[164:167], v[180:183], v[44:47]
	global_load_lds_dwordx4 v130, s[30:31]
	v_lshl_add_u64 v[218:219], s[30:31], 0, v[128:129]
	v_lshl_add_u64 v[220:221], s[30:31], 0, v[130:131]
	v_mfma_f32_16x16x32_bf16 v[40:43], v[172:175], v[180:183], v[40:43]
	v_mfma_f32_16x16x32_bf16 v[28:31], v[164:167], v[190:193], v[28:31]
	v_mfma_f32_16x16x32_bf16 v[24:27], v[172:175], v[190:193], v[24:27]
	v_mfma_f32_16x16x32_bf16 v[12:15], v[164:167], v[198:201], v[12:15]
	v_mfma_f32_16x16x32_bf16 v[8:11], v[172:175], v[198:201], v[8:11]
	v_mfma_f32_16x16x32_bf16 v[4:7], v[164:167], v[206:209], v[4:7]
	v_mfma_f32_16x16x32_bf16 v[0:3], v[172:175], v[206:209], v[0:3]
	v_mfma_f32_16x16x32_bf16 v[44:47], v[168:171], v[186:189], v[44:47]
	v_mfma_f32_16x16x32_bf16 v[40:43], v[176:179], v[186:189], v[40:43]
	v_mfma_f32_16x16x32_bf16 v[28:31], v[168:171], v[194:197], v[28:31]
	v_mfma_f32_16x16x32_bf16 v[24:27], v[176:179], v[194:197], v[24:27]
	v_mfma_f32_16x16x32_bf16 v[12:15], v[168:171], v[202:205], v[12:15]
	v_mfma_f32_16x16x32_bf16 v[8:11], v[176:179], v[202:205], v[8:11]
	v_mfma_f32_16x16x32_bf16 v[4:7], v[168:171], v[210:213], v[4:7]
	s_barrier
	v_mfma_f32_16x16x32_bf16 v[0:3], v[176:179], v[210:213], v[0:3]
	s_setprio 0
	ds_read_b128 v[144:147], v142 offset:32768
	ds_read_b128 v[148:151], v142 offset:33792
	ds_read_b128 v[152:155], v142 offset:34816
	ds_read_b128 v[156:159], v142 offset:35840
	ds_read_b128 v[164:167], v142 offset:49152
	ds_read_b128 v[168:171], v142 offset:50176
	ds_read_b128 v[172:175], v142 offset:51200
	ds_read_b128 v[176:179], v142 offset:52224
	s_add_u32 s30, s30, 0x40000
	s_addc_u32 s31, s31, 0
	s_mov_b32 m0, s37
	ds_read_b128 v[180:183], v143 offset:32768
	ds_read_b128 v[186:189], v143 offset:33792
	ds_read_b128 v[190:193], v143 offset:34816
	ds_read_b128 v[194:197], v143 offset:35840
	ds_read_b128 v[198:201], v143 offset:36864
	ds_read_b128 v[202:205], v143 offset:37888
	ds_read_b128 v[206:209], v143 offset:38912
	ds_read_b128 v[210:213], v143 offset:39936
	global_load_lds_dwordx4 v128, s[30:31]
	s_mov_b32 m0, s38
	s_nop 0
	global_load_lds_dwordx4 v130, s[30:31]
	s_waitcnt vmcnt(8)
	s_waitcnt lgkmcnt(0)
	s_barrier
	s_setprio 1
	s_waitcnt lgkmcnt(0)
	v_mfma_f32_16x16x32_bf16 v[124:127], v[144:147], v[180:183], v[124:127]
	v_mfma_f32_16x16x32_bf16 v[120:123], v[152:155], v[180:183], v[120:123]
	v_mfma_f32_16x16x32_bf16 v[116:119], v[144:147], v[190:193], v[116:119]
	v_mfma_f32_16x16x32_bf16 v[112:115], v[152:155], v[190:193], v[112:115]
	v_mfma_f32_16x16x32_bf16 v[100:103], v[144:147], v[198:201], v[100:103]
	v_mfma_f32_16x16x32_bf16 v[96:99], v[152:155], v[198:201], v[96:99]
	v_mfma_f32_16x16x32_bf16 v[84:87], v[144:147], v[206:209], v[84:87]
	v_mfma_f32_16x16x32_bf16 v[80:83], v[152:155], v[206:209], v[80:83]
	v_mfma_f32_16x16x32_bf16 v[124:127], v[148:151], v[186:189], v[124:127]
	v_mfma_f32_16x16x32_bf16 v[120:123], v[156:159], v[186:189], v[120:123]
	v_mfma_f32_16x16x32_bf16 v[116:119], v[148:151], v[194:197], v[116:119]
	v_mfma_f32_16x16x32_bf16 v[112:115], v[156:159], v[194:197], v[112:115]
	v_mfma_f32_16x16x32_bf16 v[100:103], v[148:151], v[202:205], v[100:103]
	v_mfma_f32_16x16x32_bf16 v[96:99], v[156:159], v[202:205], v[96:99]
	v_mfma_f32_16x16x32_bf16 v[84:87], v[148:151], v[210:213], v[84:87]
	v_mfma_f32_16x16x32_bf16 v[80:83], v[156:159], v[210:213], v[80:83]
	s_setprio 0
	s_setprio 1
	v_mfma_f32_16x16x32_bf16 v[108:111], v[164:167], v[180:183], v[108:111]
	v_mfma_f32_16x16x32_bf16 v[104:107], v[172:175], v[180:183], v[104:107]
	v_mfma_f32_16x16x32_bf16 v[92:95], v[164:167], v[190:193], v[92:95]
	v_mfma_f32_16x16x32_bf16 v[88:91], v[172:175], v[190:193], v[88:91]
	v_mfma_f32_16x16x32_bf16 v[76:79], v[164:167], v[198:201], v[76:79]
	v_mfma_f32_16x16x32_bf16 v[72:75], v[172:175], v[198:201], v[72:75]
	v_mfma_f32_16x16x32_bf16 v[68:71], v[164:167], v[206:209], v[68:71]
	v_mfma_f32_16x16x32_bf16 v[64:67], v[172:175], v[206:209], v[64:67]
	v_mfma_f32_16x16x32_bf16 v[108:111], v[168:171], v[186:189], v[108:111]
	v_mfma_f32_16x16x32_bf16 v[104:107], v[176:179], v[186:189], v[104:107]
	v_mfma_f32_16x16x32_bf16 v[92:95], v[168:171], v[194:197], v[92:95]
	v_mfma_f32_16x16x32_bf16 v[88:91], v[176:179], v[194:197], v[88:91]
	v_mfma_f32_16x16x32_bf16 v[76:79], v[168:171], v[202:205], v[76:79]
	v_mfma_f32_16x16x32_bf16 v[72:75], v[176:179], v[202:205], v[72:75]
	v_mfma_f32_16x16x32_bf16 v[68:71], v[168:171], v[210:213], v[68:71]
	s_barrier
	v_mfma_f32_16x16x32_bf16 v[64:67], v[176:179], v[210:213], v[64:67]
	s_setprio 0
	s_mov_b32 m0, s40
	v_lshl_add_u64 v[214:215], v[214:215], 0, s[6:7]
	ds_read_b128 v[180:183], v143 offset:49152
	ds_read_b128 v[186:189], v143 offset:50176
	ds_read_b128 v[190:193], v143 offset:51200
	ds_read_b128 v[194:197], v143 offset:52224
	ds_read_b128 v[198:201], v143 offset:53248
	ds_read_b128 v[202:205], v143 offset:54272
	ds_read_b128 v[206:209], v143 offset:55296
	ds_read_b128 v[210:213], v143 offset:56320
	global_load_lds_dwordx4 v[214:215], off
	v_lshl_add_u64 v[214:215], v[216:217], 0, s[6:7]
	s_mov_b32 m0, s41
	s_add_u32 s28, s28, 0x40080
	global_load_lds_dwordx4 v[214:215], off
	s_addc_u32 s29, s29, 0
	s_mov_b32 m0, s44
	v_lshl_add_u64 v[214:215], v[218:219], 0, s[6:7]
	global_load_lds_dwordx4 v138, s[28:29]
	s_mov_b32 m0, s45
	s_nop 0
	global_load_lds_dwordx4 v132, s[28:29]
	s_waitcnt vmcnt(6)
	s_waitcnt lgkmcnt(0)
	s_barrier
	s_setprio 1
	s_waitcnt lgkmcnt(0)
	v_mfma_f32_16x16x32_bf16 v[60:63], v[144:147], v[180:183], v[60:63]
	v_mfma_f32_16x16x32_bf16 v[56:59], v[152:155], v[180:183], v[56:59]
	s_mov_b32 m0, s42
	v_mfma_f32_16x16x32_bf16 v[52:55], v[144:147], v[190:193], v[52:55]
	global_load_lds_dwordx4 v[214:215], off
	v_mfma_f32_16x16x32_bf16 v[48:51], v[152:155], v[190:193], v[48:51]
	v_mfma_f32_16x16x32_bf16 v[36:39], v[144:147], v[198:201], v[36:39]
	v_mfma_f32_16x16x32_bf16 v[32:35], v[152:155], v[198:201], v[32:35]
	v_mfma_f32_16x16x32_bf16 v[20:23], v[144:147], v[206:209], v[20:23]
	v_mfma_f32_16x16x32_bf16 v[16:19], v[152:155], v[206:209], v[16:19]
	v_mfma_f32_16x16x32_bf16 v[60:63], v[148:151], v[186:189], v[60:63]
	v_mfma_f32_16x16x32_bf16 v[56:59], v[156:159], v[186:189], v[56:59]
	v_mfma_f32_16x16x32_bf16 v[52:55], v[148:151], v[194:197], v[52:55]
	v_mfma_f32_16x16x32_bf16 v[48:51], v[156:159], v[194:197], v[48:51]
	v_mfma_f32_16x16x32_bf16 v[36:39], v[148:151], v[202:205], v[36:39]
	v_mfma_f32_16x16x32_bf16 v[32:35], v[156:159], v[202:205], v[32:35]
	v_mfma_f32_16x16x32_bf16 v[20:23], v[148:151], v[210:213], v[20:23]
	v_mfma_f32_16x16x32_bf16 v[16:19], v[156:159], v[210:213], v[16:19]
	v_lshl_add_u64 v[214:215], v[220:221], 0, s[6:7]
	s_mov_b32 m0, s43
	s_setprio 0
	s_setprio 1
	v_mfma_f32_16x16x32_bf16 v[44:47], v[164:167], v[180:183], v[44:47]
	global_load_lds_dwordx4 v[214:215], off
	v_mfma_f32_16x16x32_bf16 v[40:43], v[172:175], v[180:183], v[40:43]
	v_mfma_f32_16x16x32_bf16 v[28:31], v[164:167], v[190:193], v[28:31]
	v_mfma_f32_16x16x32_bf16 v[24:27], v[172:175], v[190:193], v[24:27]
	v_mfma_f32_16x16x32_bf16 v[12:15], v[164:167], v[198:201], v[12:15]
	v_mfma_f32_16x16x32_bf16 v[8:11], v[172:175], v[198:201], v[8:11]
	v_mfma_f32_16x16x32_bf16 v[4:7], v[164:167], v[206:209], v[4:7]
	v_mfma_f32_16x16x32_bf16 v[0:3], v[172:175], v[206:209], v[0:3]
	v_mfma_f32_16x16x32_bf16 v[44:47], v[168:171], v[186:189], v[44:47]
	v_mfma_f32_16x16x32_bf16 v[40:43], v[176:179], v[186:189], v[40:43]
	v_mfma_f32_16x16x32_bf16 v[28:31], v[168:171], v[194:197], v[28:31]
	v_mfma_f32_16x16x32_bf16 v[24:27], v[176:179], v[194:197], v[24:27]
	v_mfma_f32_16x16x32_bf16 v[12:15], v[168:171], v[202:205], v[12:15]
	v_mfma_f32_16x16x32_bf16 v[8:11], v[176:179], v[202:205], v[8:11]
	v_mfma_f32_16x16x32_bf16 v[4:7], v[168:171], v[210:213], v[4:7]
	s_barrier
	v_mfma_f32_16x16x32_bf16 v[0:3], v[176:179], v[210:213], v[0:3]
	s_nop 0
	s_setprio 0
	s_add_i32 s53, s53, 2
	s_add_u32 s26, s26, 0x100
	s_addc_u32 s27, s27, 0
	s_add_u32 s51, s51, 0x100
	s_addc_u32 s52, s52, 0
	s_cmp_gt_u32 s53, 13
	s_cbranch_scc0 .LBB0_206
	s_and_b64 vcc, exec, s[8:9]
	s_cbranch_vccz .LBB0_209
	s_barrier

.LBB0_459:
	ds_read_b128 v[144:147], v142
	ds_read_b128 v[148:151], v142 offset:1024
	ds_read_b128 v[152:155], v142 offset:2048
	ds_read_b128 v[156:159], v142 offset:3072
	ds_read_b128 v[164:167], v142 offset:16384
	ds_read_b128 v[168:171], v142 offset:17408
	ds_read_b128 v[172:175], v142 offset:18432
	ds_read_b128 v[176:179], v142 offset:19456
	s_add_u32 s23, s26, 0xfff80080
	s_addc_u32 s28, s27, -1
	s_cmp_eq_u32 s54, 28
	s_cselect_b32 s31, s13, s28
	s_cselect_b32 s30, s50, s23
	s_cselect_b32 s29, s11, s53
	s_cselect_b32 s28, s51, s52
	s_add_i32 m0, s15, 0xc000
	ds_read_b128 v[180:183], v143
	ds_read_b128 v[188:191], v143 offset:1024
	ds_read_b128 v[192:195], v143 offset:2048
	ds_read_b128 v[196:199], v143 offset:3072
	ds_read_b128 v[200:203], v143 offset:4096
	ds_read_b128 v[204:207], v143 offset:5120
	ds_read_b128 v[208:211], v143 offset:6144
	ds_read_b128 v[212:215], v143 offset:7168
	global_load_lds_dwordx4 v128, s[26:27]
	s_add_i32 m0, s15, 0xe000
	v_mov_b32_e32 v131, v129
	global_load_lds_dwordx4 v130, s[26:27]
	s_waitcnt vmcnt(8)
	s_waitcnt lgkmcnt(0)
	s_barrier
	s_setprio 1
	s_waitcnt lgkmcnt(0)
	v_mfma_f32_16x16x32_bf16 v[124:127], v[144:147], v[180:183], v[124:127]
	v_mfma_f32_16x16x32_bf16 v[120:123], v[152:155], v[180:183], v[120:123]
	v_mfma_f32_16x16x32_bf16 v[116:119], v[144:147], v[192:195], v[116:119]
	v_mfma_f32_16x16x32_bf16 v[112:115], v[152:155], v[192:195], v[112:115]
	v_mfma_f32_16x16x32_bf16 v[100:103], v[144:147], v[200:203], v[100:103]
	v_mfma_f32_16x16x32_bf16 v[96:99], v[152:155], v[200:203], v[96:99]
	v_mfma_f32_16x16x32_bf16 v[84:87], v[144:147], v[208:211], v[84:87]
	v_mfma_f32_16x16x32_bf16 v[80:83], v[152:155], v[208:211], v[80:83]
	v_mfma_f32_16x16x32_bf16 v[124:127], v[148:151], v[188:191], v[124:127]
	v_mfma_f32_16x16x32_bf16 v[120:123], v[156:159], v[188:191], v[120:123]
	v_mfma_f32_16x16x32_bf16 v[116:119], v[148:151], v[196:199], v[116:119]
	v_mfma_f32_16x16x32_bf16 v[112:115], v[156:159], v[196:199], v[112:115]
	v_mfma_f32_16x16x32_bf16 v[100:103], v[148:151], v[204:207], v[100:103]
	v_mfma_f32_16x16x32_bf16 v[96:99], v[156:159], v[204:207], v[96:99]
	v_mfma_f32_16x16x32_bf16 v[84:87], v[148:151], v[212:215], v[84:87]
	v_mfma_f32_16x16x32_bf16 v[80:83], v[156:159], v[212:215], v[80:83]
	s_setprio 0
	s_setprio 1
	v_mfma_f32_16x16x32_bf16 v[108:111], v[164:167], v[180:183], v[108:111]
	v_mfma_f32_16x16x32_bf16 v[104:107], v[172:175], v[180:183], v[104:107]
	v_mfma_f32_16x16x32_bf16 v[92:95], v[164:167], v[192:195], v[92:95]
	v_mfma_f32_16x16x32_bf16 v[88:91], v[172:175], v[192:195], v[88:91]
	v_mfma_f32_16x16x32_bf16 v[76:79], v[164:167], v[200:203], v[76:79]
	v_mfma_f32_16x16x32_bf16 v[72:75], v[172:175], v[200:203], v[72:75]
	v_mfma_f32_16x16x32_bf16 v[68:71], v[164:167], v[208:211], v[68:71]
	v_mfma_f32_16x16x32_bf16 v[64:67], v[172:175], v[208:211], v[64:67]
	v_mfma_f32_16x16x32_bf16 v[108:111], v[168:171], v[188:191], v[108:111]
	v_mfma_f32_16x16x32_bf16 v[104:107], v[176:179], v[188:191], v[104:107]
	v_mfma_f32_16x16x32_bf16 v[92:95], v[168:171], v[196:199], v[92:95]
	v_mfma_f32_16x16x32_bf16 v[88:91], v[176:179], v[196:199], v[88:91]
	v_mfma_f32_16x16x32_bf16 v[76:79], v[168:171], v[204:207], v[76:79]
	v_mfma_f32_16x16x32_bf16 v[72:75], v[176:179], v[204:207], v[72:75]
	v_mfma_f32_16x16x32_bf16 v[68:71], v[168:171], v[212:215], v[68:71]
	s_barrier
	v_mfma_f32_16x16x32_bf16 v[64:67], v[176:179], v[212:215], v[64:67]
	s_setprio 0
	s_mov_b32 m0, s34
	ds_read_b128 v[180:183], v143 offset:16384
	ds_read_b128 v[188:191], v143 offset:17408
	ds_read_b128 v[192:195], v143 offset:18432
	ds_read_b128 v[196:199], v143 offset:19456
	ds_read_b128 v[200:203], v143 offset:20480
	ds_read_b128 v[204:207], v143 offset:21504
	ds_read_b128 v[208:211], v143 offset:22528
	ds_read_b128 v[212:215], v143 offset:23552
	global_load_lds_dwordx4 v138, s[28:29]
	s_mov_b32 m0, s35
	s_add_u32 s86, s28, 0x80000
	global_load_lds_dwordx4 v132, s[28:29]
	s_addc_u32 s87, s29, 0
	s_mov_b32 m0, s36
	v_mov_b32_e32 v139, v129
	global_load_lds_dwordx4 v138, s[86:87]
	s_mov_b32 m0, s37
	v_mov_b32_e32 v133, v129
	global_load_lds_dwordx4 v132, s[86:87]
	s_waitcnt vmcnt(6)
	s_waitcnt lgkmcnt(0)
	s_barrier
	s_setprio 1
	s_waitcnt lgkmcnt(0)
	v_mfma_f32_16x16x32_bf16 v[60:63], v[144:147], v[180:183], v[60:63]
	v_mfma_f32_16x16x32_bf16 v[56:59], v[152:155], v[180:183], v[56:59]
	s_mov_b32 m0, s15
	v_lshl_add_u64 v[216:217], s[28:29], 0, v[138:139]
	v_mfma_f32_16x16x32_bf16 v[52:55], v[144:147], v[192:195], v[52:55]
	global_load_lds_dwordx4 v128, s[30:31]
	v_mfma_f32_16x16x32_bf16 v[48:51], v[152:155], v[192:195], v[48:51]
	v_mfma_f32_16x16x32_bf16 v[36:39], v[144:147], v[200:203], v[36:39]
	v_mfma_f32_16x16x32_bf16 v[32:35], v[152:155], v[200:203], v[32:35]
	v_mfma_f32_16x16x32_bf16 v[20:23], v[144:147], v[208:211], v[20:23]
	v_mfma_f32_16x16x32_bf16 v[16:19], v[152:155], v[208:211], v[16:19]
	v_mfma_f32_16x16x32_bf16 v[60:63], v[148:151], v[188:191], v[60:63]
	v_mfma_f32_16x16x32_bf16 v[56:59], v[156:159], v[188:191], v[56:59]
	v_mfma_f32_16x16x32_bf16 v[52:55], v[148:151], v[196:199], v[52:55]
	v_mfma_f32_16x16x32_bf16 v[48:51], v[156:159], v[196:199], v[48:51]
	v_mfma_f32_16x16x32_bf16 v[36:39], v[148:151], v[204:207], v[36:39]
	v_mfma_f32_16x16x32_bf16 v[32:35], v[156:159], v[204:207], v[32:35]
	v_mfma_f32_16x16x32_bf16 v[20:23], v[148:151], v[212:215], v[20:23]
	v_mfma_f32_16x16x32_bf16 v[16:19], v[156:159], v[212:215], v[16:19]
	s_mov_b32 m0, s38
	v_lshl_add_u64 v[218:219], s[28:29], 0, v[132:133]
	s_setprio 0
	s_setprio 1
	v_mfma_f32_16x16x32_bf16 v[44:47], v[164:167], v[180:183], v[44:47]
	global_load_lds_dwordx4 v130, s[30:31]
	v_lshl_add_u64 v[220:221], s[30:31], 0, v[128:129]
	v_lshl_add_u64 v[222:223], s[30:31], 0, v[130:131]
	v_mfma_f32_16x16x32_bf16 v[40:43], v[172:175], v[180:183], v[40:43]
	v_mfma_f32_16x16x32_bf16 v[28:31], v[164:167], v[192:195], v[28:31]
	v_mfma_f32_16x16x32_bf16 v[24:27], v[172:175], v[192:195], v[24:27]
	v_mfma_f32_16x16x32_bf16 v[12:15], v[164:167], v[200:203], v[12:15]
	v_mfma_f32_16x16x32_bf16 v[8:11], v[172:175], v[200:203], v[8:11]
	v_mfma_f32_16x16x32_bf16 v[4:7], v[164:167], v[208:211], v[4:7]
	v_mfma_f32_16x16x32_bf16 v[0:3], v[172:175], v[208:211], v[0:3]
	v_mfma_f32_16x16x32_bf16 v[44:47], v[168:171], v[188:191], v[44:47]
	v_mfma_f32_16x16x32_bf16 v[40:43], v[176:179], v[188:191], v[40:43]
	v_mfma_f32_16x16x32_bf16 v[28:31], v[168:171], v[196:199], v[28:31]
	v_mfma_f32_16x16x32_bf16 v[24:27], v[176:179], v[196:199], v[24:27]
	v_mfma_f32_16x16x32_bf16 v[12:15], v[168:171], v[204:207], v[12:15]
	v_mfma_f32_16x16x32_bf16 v[8:11], v[176:179], v[204:207], v[8:11]
	v_mfma_f32_16x16x32_bf16 v[4:7], v[168:171], v[212:215], v[4:7]
	s_barrier
	v_mfma_f32_16x16x32_bf16 v[0:3], v[176:179], v[212:215], v[0:3]
	s_setprio 0
	ds_read_b128 v[144:147], v142 offset:32768
	ds_read_b128 v[148:151], v142 offset:33792
	ds_read_b128 v[152:155], v142 offset:34816
	ds_read_b128 v[156:159], v142 offset:35840
	ds_read_b128 v[164:167], v142 offset:49152
	ds_read_b128 v[168:171], v142 offset:50176
	ds_read_b128 v[172:175], v142 offset:51200
	ds_read_b128 v[176:179], v142 offset:52224
	s_add_u32 s30, s30, 0x80000
	s_addc_u32 s31, s31, 0
	s_mov_b32 m0, s39
	ds_read_b128 v[180:183], v143 offset:32768
	ds_read_b128 v[188:191], v143 offset:33792
	ds_read_b128 v[192:195], v143 offset:34816
	ds_read_b128 v[196:199], v143 offset:35840
	ds_read_b128 v[200:203], v143 offset:36864
	ds_read_b128 v[204:207], v143 offset:37888
	ds_read_b128 v[208:211], v143 offset:38912
	ds_read_b128 v[212:215], v143 offset:39936
	global_load_lds_dwordx4 v128, s[30:31]
	s_mov_b32 m0, s40
	s_nop 0
	global_load_lds_dwordx4 v130, s[30:31]
	s_waitcnt vmcnt(8)
	s_waitcnt lgkmcnt(0)
	s_barrier
	s_setprio 1
	s_waitcnt lgkmcnt(0)
	v_mfma_f32_16x16x32_bf16 v[124:127], v[144:147], v[180:183], v[124:127]
	v_mfma_f32_16x16x32_bf16 v[120:123], v[152:155], v[180:183], v[120:123]
	v_mfma_f32_16x16x32_bf16 v[116:119], v[144:147], v[192:195], v[116:119]
	v_mfma_f32_16x16x32_bf16 v[112:115], v[152:155], v[192:195], v[112:115]
	v_mfma_f32_16x16x32_bf16 v[100:103], v[144:147], v[200:203], v[100:103]
	v_mfma_f32_16x16x32_bf16 v[96:99], v[152:155], v[200:203], v[96:99]
	v_mfma_f32_16x16x32_bf16 v[84:87], v[144:147], v[208:211], v[84:87]
	v_mfma_f32_16x16x32_bf16 v[80:83], v[152:155], v[208:211], v[80:83]
	v_mfma_f32_16x16x32_bf16 v[124:127], v[148:151], v[188:191], v[124:127]
	v_mfma_f32_16x16x32_bf16 v[120:123], v[156:159], v[188:191], v[120:123]
	v_mfma_f32_16x16x32_bf16 v[116:119], v[148:151], v[196:199], v[116:119]
	v_mfma_f32_16x16x32_bf16 v[112:115], v[156:159], v[196:199], v[112:115]
	v_mfma_f32_16x16x32_bf16 v[100:103], v[148:151], v[204:207], v[100:103]
	v_mfma_f32_16x16x32_bf16 v[96:99], v[156:159], v[204:207], v[96:99]
	v_mfma_f32_16x16x32_bf16 v[84:87], v[148:151], v[212:215], v[84:87]
	v_mfma_f32_16x16x32_bf16 v[80:83], v[156:159], v[212:215], v[80:83]
	s_setprio 0
	s_setprio 1
	v_mfma_f32_16x16x32_bf16 v[108:111], v[164:167], v[180:183], v[108:111]
	v_mfma_f32_16x16x32_bf16 v[104:107], v[172:175], v[180:183], v[104:107]
	v_mfma_f32_16x16x32_bf16 v[92:95], v[164:167], v[192:195], v[92:95]
	v_mfma_f32_16x16x32_bf16 v[88:91], v[172:175], v[192:195], v[88:91]
	v_mfma_f32_16x16x32_bf16 v[76:79], v[164:167], v[200:203], v[76:79]
	v_mfma_f32_16x16x32_bf16 v[72:75], v[172:175], v[200:203], v[72:75]
	v_mfma_f32_16x16x32_bf16 v[68:71], v[164:167], v[208:211], v[68:71]
	v_mfma_f32_16x16x32_bf16 v[64:67], v[172:175], v[208:211], v[64:67]
	v_mfma_f32_16x16x32_bf16 v[108:111], v[168:171], v[188:191], v[108:111]
	v_mfma_f32_16x16x32_bf16 v[104:107], v[176:179], v[188:191], v[104:107]
	v_mfma_f32_16x16x32_bf16 v[92:95], v[168:171], v[196:199], v[92:95]
	v_mfma_f32_16x16x32_bf16 v[88:91], v[176:179], v[196:199], v[88:91]
	v_mfma_f32_16x16x32_bf16 v[76:79], v[168:171], v[204:207], v[76:79]
	v_mfma_f32_16x16x32_bf16 v[72:75], v[176:179], v[204:207], v[72:75]
	v_mfma_f32_16x16x32_bf16 v[68:71], v[168:171], v[212:215], v[68:71]
	s_barrier
	v_mfma_f32_16x16x32_bf16 v[64:67], v[176:179], v[212:215], v[64:67]
	s_setprio 0
	s_mov_b32 m0, s42
	v_lshl_add_u64 v[216:217], v[216:217], 0, s[6:7]
	ds_read_b128 v[180:183], v143 offset:49152
	ds_read_b128 v[188:191], v143 offset:50176
	ds_read_b128 v[192:195], v143 offset:51200
	ds_read_b128 v[196:199], v143 offset:52224
	ds_read_b128 v[200:203], v143 offset:53248
	ds_read_b128 v[204:207], v143 offset:54272
	ds_read_b128 v[208:211], v143 offset:55296
	ds_read_b128 v[212:215], v143 offset:56320
	global_load_lds_dwordx4 v[216:217], off
	v_lshl_add_u64 v[216:217], v[218:219], 0, s[6:7]
	s_mov_b32 m0, s43
	s_add_u32 s28, s28, 0x80080
	global_load_lds_dwordx4 v[216:217], off
	s_addc_u32 s29, s29, 0
	s_mov_b32 m0, s47
	v_lshl_add_u64 v[216:217], v[220:221], 0, s[6:7]
	global_load_lds_dwordx4 v138, s[28:29]
	s_mov_b32 m0, s48
	s_nop 0
	global_load_lds_dwordx4 v132, s[28:29]
	s_waitcnt vmcnt(6)
	s_waitcnt lgkmcnt(0)
	s_barrier
	s_setprio 1
	s_waitcnt lgkmcnt(0)
	v_mfma_f32_16x16x32_bf16 v[60:63], v[144:147], v[180:183], v[60:63]
	v_mfma_f32_16x16x32_bf16 v[56:59], v[152:155], v[180:183], v[56:59]
	s_mov_b32 m0, s44
	v_mfma_f32_16x16x32_bf16 v[52:55], v[144:147], v[192:195], v[52:55]
	global_load_lds_dwordx4 v[216:217], off
	v_mfma_f32_16x16x32_bf16 v[48:51], v[152:155], v[192:195], v[48:51]
	v_mfma_f32_16x16x32_bf16 v[36:39], v[144:147], v[200:203], v[36:39]
	v_mfma_f32_16x16x32_bf16 v[32:35], v[152:155], v[200:203], v[32:35]
	v_mfma_f32_16x16x32_bf16 v[20:23], v[144:147], v[208:211], v[20:23]
	v_mfma_f32_16x16x32_bf16 v[16:19], v[152:155], v[208:211], v[16:19]
	v_mfma_f32_16x16x32_bf16 v[60:63], v[148:151], v[188:191], v[60:63]
	v_mfma_f32_16x16x32_bf16 v[56:59], v[156:159], v[188:191], v[56:59]
	v_mfma_f32_16x16x32_bf16 v[52:55], v[148:151], v[196:199], v[52:55]
	v_mfma_f32_16x16x32_bf16 v[48:51], v[156:159], v[196:199], v[48:51]
	v_mfma_f32_16x16x32_bf16 v[36:39], v[148:151], v[204:207], v[36:39]
	v_mfma_f32_16x16x32_bf16 v[32:35], v[156:159], v[204:207], v[32:35]
	v_mfma_f32_16x16x32_bf16 v[20:23], v[148:151], v[212:215], v[20:23]
	v_mfma_f32_16x16x32_bf16 v[16:19], v[156:159], v[212:215], v[16:19]
	v_lshl_add_u64 v[216:217], v[222:223], 0, s[6:7]
	s_mov_b32 m0, s45
	s_setprio 0
	s_setprio 1
	v_mfma_f32_16x16x32_bf16 v[44:47], v[164:167], v[180:183], v[44:47]
	global_load_lds_dwordx4 v[216:217], off
	v_mfma_f32_16x16x32_bf16 v[40:43], v[172:175], v[180:183], v[40:43]
	v_mfma_f32_16x16x32_bf16 v[28:31], v[164:167], v[192:195], v[28:31]
	v_mfma_f32_16x16x32_bf16 v[24:27], v[172:175], v[192:195], v[24:27]
	v_mfma_f32_16x16x32_bf16 v[12:15], v[164:167], v[200:203], v[12:15]
	v_mfma_f32_16x16x32_bf16 v[8:11], v[172:175], v[200:203], v[8:11]
	v_mfma_f32_16x16x32_bf16 v[4:7], v[164:167], v[208:211], v[4:7]
	v_mfma_f32_16x16x32_bf16 v[0:3], v[172:175], v[208:211], v[0:3]
	v_mfma_f32_16x16x32_bf16 v[44:47], v[168:171], v[188:191], v[44:47]
	v_mfma_f32_16x16x32_bf16 v[40:43], v[176:179], v[188:191], v[40:43]
	v_mfma_f32_16x16x32_bf16 v[28:31], v[168:171], v[196:199], v[28:31]
	v_mfma_f32_16x16x32_bf16 v[24:27], v[176:179], v[196:199], v[24:27]
	v_mfma_f32_16x16x32_bf16 v[12:15], v[168:171], v[204:207], v[12:15]
	v_mfma_f32_16x16x32_bf16 v[8:11], v[176:179], v[204:207], v[8:11]
	v_mfma_f32_16x16x32_bf16 v[4:7], v[168:171], v[212:215], v[4:7]
	s_barrier
	v_mfma_f32_16x16x32_bf16 v[0:3], v[176:179], v[212:215], v[0:3]
	s_nop 0
	s_setprio 0
	s_add_i32 s54, s54, 2
	s_add_u32 s26, s26, 0x100
	s_addc_u32 s27, s27, 0
	s_add_u32 s52, s52, 0x100
	s_addc_u32 s53, s53, 0
	s_cmp_gt_u32 s54, 29
	s_cbranch_scc0 .LBB0_459
	s_and_b64 vcc, exec, s[8:9]
	s_cbranch_vccz .LBB0_462
	s_barrier

.LBB0_585:
	ds_read_b128 v[24:27], v189
	ds_read_b128 v[28:31], v189 offset:16
	ds_read_b128 v[16:19], v189 offset:2048
	ds_read_b128 v[20:23], v189 offset:2064
	ds_read_b128 v[8:11], v189 offset:16384
	ds_read_b128 v[12:15], v189 offset:16400
	ds_read_b128 v[0:3], v189 offset:18432
	ds_read_b128 v[4:7], v189 offset:18448
	s_add_u32 s23, s30, 0xfffe0080
	s_addc_u32 s34, s31, -1
	s_cmp_eq_u32 s64, 4
	s_cselect_b32 s37, s21, s34
	s_cselect_b32 s36, s53, s23
	s_cselect_b32 s35, s15, s63
	s_cselect_b32 s34, s54, s55
	s_add_i32 m0, s11, 0xc000
	ds_read_b128 v[176:179], v190
	ds_read_b128 v[180:183], v190 offset:16
	ds_read_b128 v[192:195], v190 offset:2048
	ds_read_b128 v[196:199], v190 offset:2064
	ds_read_b128 v[200:203], v190 offset:4096
	ds_read_b128 v[204:207], v190 offset:4112
	ds_read_b128 v[208:211], v190 offset:6144
	ds_read_b128 v[212:215], v190 offset:6160
	global_load_lds_dwordx4 v164, s[30:31]
	s_add_i32 m0, s11, 0xe000
	v_mov_b32_e32 v169, v165
	global_load_lds_dwordx4 v168, s[30:31]
	s_waitcnt vmcnt(8)
	s_waitcnt lgkmcnt(0)
	s_barrier
	s_setprio 1
	s_waitcnt lgkmcnt(0)
	v_mfma_f32_16x16x128_f8f6f4 v[156:159], v[24:31], v[176:183], v[156:159]
	v_mfma_f32_16x16x128_f8f6f4 v[148:151], v[16:23], v[176:183], v[148:151]
	v_mfma_f32_16x16x128_f8f6f4 v[140:143], v[24:31], v[192:199], v[140:143]
	v_mfma_f32_16x16x128_f8f6f4 v[132:135], v[16:23], v[192:199], v[132:135]
	v_mfma_f32_16x16x128_f8f6f4 v[124:127], v[24:31], v[200:207], v[124:127]
	v_mfma_f32_16x16x128_f8f6f4 v[116:119], v[16:23], v[200:207], v[116:119]
	v_mfma_f32_16x16x128_f8f6f4 v[108:111], v[24:31], v[208:215], v[108:111]
	v_mfma_f32_16x16x128_f8f6f4 v[100:103], v[16:23], v[208:215], v[100:103]
	s_setprio 0
	s_setprio 1
	v_mfma_f32_16x16x128_f8f6f4 v[152:155], v[8:15], v[176:183], v[152:155]
	v_mfma_f32_16x16x128_f8f6f4 v[144:147], v[0:7], v[176:183], v[144:147]
	v_mfma_f32_16x16x128_f8f6f4 v[136:139], v[8:15], v[192:199], v[136:139]
	v_mfma_f32_16x16x128_f8f6f4 v[128:131], v[0:7], v[192:199], v[128:131]
	v_mfma_f32_16x16x128_f8f6f4 v[120:123], v[8:15], v[200:207], v[120:123]
	v_mfma_f32_16x16x128_f8f6f4 v[112:115], v[0:7], v[200:207], v[112:115]
	v_mfma_f32_16x16x128_f8f6f4 v[104:107], v[8:15], v[208:215], v[104:107]
	s_barrier
	v_mfma_f32_16x16x128_f8f6f4 v[96:99], v[0:7], v[208:215], v[96:99]
	s_setprio 0
	s_mov_b32 m0, s13
	ds_read_b128 v[192:195], v190 offset:16384
	ds_read_b128 v[196:199], v190 offset:16400
	ds_read_b128 v[200:203], v190 offset:18432
	ds_read_b128 v[204:207], v190 offset:18448
	ds_read_b128 v[208:211], v190 offset:20480
	ds_read_b128 v[212:215], v190 offset:20496
	ds_read_b128 v[216:219], v190 offset:22528
	ds_read_b128 v[220:223], v190 offset:22544
	global_load_lds_dwordx4 v166, s[34:35]
	s_mov_b32 m0, s22
	s_add_u32 s86, s34, 0x20000
	global_load_lds_dwordx4 v170, s[34:35]
	s_addc_u32 s87, s35, 0
	s_mov_b32 m0, s29
	v_mov_b32_e32 v167, v165
	global_load_lds_dwordx4 v166, s[86:87]
	s_mov_b32 m0, s38
	v_mov_b32_e32 v171, v165
	global_load_lds_dwordx4 v170, s[86:87]
	s_waitcnt vmcnt(6)
	s_waitcnt lgkmcnt(0)
	s_barrier
	s_setprio 1
	s_waitcnt lgkmcnt(0)
	v_mfma_f32_16x16x128_f8f6f4 v[92:95], v[24:31], v[192:199], v[92:95]
	v_mfma_f32_16x16x128_f8f6f4 v[84:87], v[16:23], v[192:199], v[84:87]
	s_mov_b32 m0, s11
	v_lshl_add_u64 v[182:183], s[34:35], 0, v[166:167]
	v_mfma_f32_16x16x128_f8f6f4 v[76:79], v[24:31], v[200:207], v[76:79]
	global_load_lds_dwordx4 v164, s[36:37]
	v_mfma_f32_16x16x128_f8f6f4 v[68:71], v[16:23], v[200:207], v[68:71]
	v_mfma_f32_16x16x128_f8f6f4 v[60:63], v[24:31], v[208:215], v[60:63]
	v_mfma_f32_16x16x128_f8f6f4 v[52:55], v[16:23], v[208:215], v[52:55]
	v_mfma_f32_16x16x128_f8f6f4 v[44:47], v[24:31], v[216:223], v[44:47]
	v_mfma_f32_16x16x128_f8f6f4 v[36:39], v[16:23], v[216:223], v[36:39]
	s_mov_b32 m0, s39
	v_lshl_add_u64 v[180:181], s[34:35], 0, v[170:171]
	s_setprio 0
	s_setprio 1
	v_mfma_f32_16x16x128_f8f6f4 v[88:91], v[8:15], v[192:199], v[88:91]
	global_load_lds_dwordx4 v168, s[36:37]
	v_lshl_add_u64 v[178:179], s[36:37], 0, v[164:165]
	v_lshl_add_u64 v[176:177], s[36:37], 0, v[168:169]
	v_mfma_f32_16x16x128_f8f6f4 v[80:83], v[0:7], v[192:199], v[80:83]
	v_mfma_f32_16x16x128_f8f6f4 v[72:75], v[8:15], v[200:207], v[72:75]
	v_mfma_f32_16x16x128_f8f6f4 v[64:67], v[0:7], v[200:207], v[64:67]
	v_mfma_f32_16x16x128_f8f6f4 v[56:59], v[8:15], v[208:215], v[56:59]
	v_mfma_f32_16x16x128_f8f6f4 v[48:51], v[0:7], v[208:215], v[48:51]
	v_mfma_f32_16x16x128_f8f6f4 v[40:43], v[8:15], v[216:223], v[40:43]
	s_barrier
	v_mfma_f32_16x16x128_f8f6f4 v[32:35], v[0:7], v[216:223], v[32:35]
	s_setprio 0
	ds_read_b128 v[0:3], v189 offset:32768
	ds_read_b128 v[4:7], v189 offset:32784
	ds_read_b128 v[8:11], v189 offset:34816
	ds_read_b128 v[12:15], v189 offset:34832
	ds_read_b128 v[16:19], v189 offset:49152
	ds_read_b128 v[20:23], v189 offset:49168
	ds_read_b128 v[24:27], v189 offset:51200
	ds_read_b128 v[28:31], v189 offset:51216
	s_add_u32 s36, s36, 0x20000
	s_addc_u32 s37, s37, 0
	s_mov_b32 m0, s40
	ds_read_b128 v[192:195], v190 offset:32768
	ds_read_b128 v[196:199], v190 offset:32784
	ds_read_b128 v[200:203], v190 offset:34816
	ds_read_b128 v[204:207], v190 offset:34832
	ds_read_b128 v[208:211], v190 offset:36864
	ds_read_b128 v[212:215], v190 offset:36880
	ds_read_b128 v[216:219], v190 offset:38912
	ds_read_b128 v[220:223], v190 offset:38928
	global_load_lds_dwordx4 v164, s[36:37]
	s_mov_b32 m0, s41
	s_nop 0
	global_load_lds_dwordx4 v168, s[36:37]
	s_waitcnt vmcnt(8)
	s_waitcnt lgkmcnt(0)
	s_barrier
	s_setprio 1
	s_waitcnt lgkmcnt(0)
	v_mfma_f32_16x16x128_f8f6f4 v[156:159], v[0:7], v[192:199], v[156:159]
	v_mfma_f32_16x16x128_f8f6f4 v[148:151], v[8:15], v[192:199], v[148:151]
	v_mfma_f32_16x16x128_f8f6f4 v[140:143], v[0:7], v[200:207], v[140:143]
	v_mfma_f32_16x16x128_f8f6f4 v[132:135], v[8:15], v[200:207], v[132:135]
	v_mfma_f32_16x16x128_f8f6f4 v[124:127], v[0:7], v[208:215], v[124:127]
	v_mfma_f32_16x16x128_f8f6f4 v[116:119], v[8:15], v[208:215], v[116:119]
	v_mfma_f32_16x16x128_f8f6f4 v[108:111], v[0:7], v[216:223], v[108:111]
	v_mfma_f32_16x16x128_f8f6f4 v[100:103], v[8:15], v[216:223], v[100:103]
	s_setprio 0
	s_setprio 1
	v_mfma_f32_16x16x128_f8f6f4 v[152:155], v[16:23], v[192:199], v[152:155]
	v_mfma_f32_16x16x128_f8f6f4 v[144:147], v[24:31], v[192:199], v[144:147]
	v_mfma_f32_16x16x128_f8f6f4 v[136:139], v[16:23], v[200:207], v[136:139]
	v_mfma_f32_16x16x128_f8f6f4 v[128:131], v[24:31], v[200:207], v[128:131]
	v_mfma_f32_16x16x128_f8f6f4 v[120:123], v[16:23], v[208:215], v[120:123]
	v_mfma_f32_16x16x128_f8f6f4 v[112:115], v[24:31], v[208:215], v[112:115]
	v_mfma_f32_16x16x128_f8f6f4 v[104:107], v[16:23], v[216:223], v[104:107]
	s_barrier
	v_mfma_f32_16x16x128_f8f6f4 v[96:99], v[24:31], v[216:223], v[96:99]
	s_setprio 0
	s_mov_b32 m0, s43
	v_lshl_add_u64 v[182:183], v[182:183], 0, s[6:7]
	ds_read_b128 v[192:195], v190 offset:49152
	ds_read_b128 v[196:199], v190 offset:49168
	ds_read_b128 v[200:203], v190 offset:51200
	ds_read_b128 v[204:207], v190 offset:51216
	ds_read_b128 v[208:211], v190 offset:53248
	ds_read_b128 v[212:215], v190 offset:53264
	ds_read_b128 v[216:219], v190 offset:55296
	ds_read_b128 v[220:223], v190 offset:55312
	global_load_lds_dwordx4 v[182:183], off
	v_lshl_add_u64 v[180:181], v[180:181], 0, s[6:7]
	s_mov_b32 m0, s44
	s_add_u32 s34, s34, 0x20080
	global_load_lds_dwordx4 v[180:181], off
	s_addc_u32 s35, s35, 0
	s_mov_b32 m0, s48
	v_lshl_add_u64 v[178:179], v[178:179], 0, s[6:7]
	global_load_lds_dwordx4 v166, s[34:35]
	s_mov_b32 m0, s49
	v_lshl_add_u64 v[176:177], v[176:177], 0, s[6:7]
	global_load_lds_dwordx4 v170, s[34:35]
	s_waitcnt vmcnt(6)
	s_waitcnt lgkmcnt(0)
	s_barrier
	s_setprio 1
	s_waitcnt lgkmcnt(0)
	v_mfma_f32_16x16x128_f8f6f4 v[92:95], v[0:7], v[192:199], v[92:95]
	v_mfma_f32_16x16x128_f8f6f4 v[84:87], v[8:15], v[192:199], v[84:87]
	s_mov_b32 m0, s45
	v_mfma_f32_16x16x128_f8f6f4 v[76:79], v[0:7], v[200:207], v[76:79]
	global_load_lds_dwordx4 v[178:179], off
	v_mfma_f32_16x16x128_f8f6f4 v[68:71], v[8:15], v[200:207], v[68:71]
	v_mfma_f32_16x16x128_f8f6f4 v[60:63], v[0:7], v[208:215], v[60:63]
	v_mfma_f32_16x16x128_f8f6f4 v[52:55], v[8:15], v[208:215], v[52:55]
	v_mfma_f32_16x16x128_f8f6f4 v[44:47], v[0:7], v[216:223], v[44:47]
	v_mfma_f32_16x16x128_f8f6f4 v[36:39], v[8:15], v[216:223], v[36:39]
	s_mov_b32 m0, s47
	s_setprio 0
	s_setprio 1
	v_mfma_f32_16x16x128_f8f6f4 v[88:91], v[16:23], v[192:199], v[88:91]
	global_load_lds_dwordx4 v[176:177], off
	v_mfma_f32_16x16x128_f8f6f4 v[80:83], v[24:31], v[192:199], v[80:83]
	v_mfma_f32_16x16x128_f8f6f4 v[72:75], v[16:23], v[200:207], v[72:75]
	v_mfma_f32_16x16x128_f8f6f4 v[64:67], v[24:31], v[200:207], v[64:67]
	v_mfma_f32_16x16x128_f8f6f4 v[56:59], v[16:23], v[208:215], v[56:59]
	v_mfma_f32_16x16x128_f8f6f4 v[48:51], v[24:31], v[208:215], v[48:51]
	v_mfma_f32_16x16x128_f8f6f4 v[40:43], v[16:23], v[216:223], v[40:43]
	s_barrier
	v_mfma_f32_16x16x128_f8f6f4 v[32:35], v[24:31], v[216:223], v[32:35]
	s_nop 0
	s_setprio 0
	s_add_i32 s64, s64, 2
	s_add_u32 s30, s30, 0x100
	s_addc_u32 s31, s31, 0
	s_add_u32 s55, s55, 0x100
	s_addc_u32 s63, s63, 0
	s_cmp_gt_u32 s64, 5
	s_cbranch_scc0 .LBB0_585
	s_nop 15
	s_nop 15
	s_and_b64 vcc, exec, s[8:9]
	s_cbranch_vccz .LBB0_588
	s_barrier

.LBB0_662:
	ds_read_b128 v[24:27], v189
	ds_read_b128 v[28:31], v189 offset:16
	ds_read_b128 v[16:19], v189 offset:2048
	ds_read_b128 v[20:23], v189 offset:2064
	ds_read_b128 v[8:11], v189 offset:16384
	ds_read_b128 v[12:15], v189 offset:16400
	ds_read_b128 v[0:3], v189 offset:18432
	ds_read_b128 v[4:7], v189 offset:18448
	s_add_u32 s24, s20, 0xfffa8080
	s_addc_u32 s25, s21, -1
	s_cmp_eq_u32 s48, 18
	s_cselect_b32 s27, s1, s25
	s_cselect_b32 s26, s0, s24
	s_cselect_b32 s25, s15, s47
	s_cselect_b32 s24, s14, s45
	s_add_i32 m0, s3, 0xc000
	ds_read_b128 v[176:179], v190
	ds_read_b128 v[180:183], v190 offset:16
	ds_read_b128 v[192:195], v190 offset:2048
	ds_read_b128 v[196:199], v190 offset:2064
	ds_read_b128 v[200:203], v190 offset:4096
	ds_read_b128 v[204:207], v190 offset:4112
	ds_read_b128 v[208:211], v190 offset:6144
	ds_read_b128 v[212:215], v190 offset:6160
	global_load_lds_dwordx4 v164, s[20:21]
	s_add_i32 m0, s3, 0xe000
	v_mov_b32_e32 v169, v165
	global_load_lds_dwordx4 v168, s[20:21]
	s_waitcnt vmcnt(8)
	s_waitcnt lgkmcnt(0)
	s_barrier
	s_setprio 1
	s_waitcnt lgkmcnt(0)
	v_mfma_f32_16x16x128_f8f6f4 v[156:159], v[24:31], v[176:183], v[156:159]
	v_mfma_f32_16x16x128_f8f6f4 v[152:155], v[16:23], v[176:183], v[152:155]
	v_mfma_f32_16x16x128_f8f6f4 v[148:151], v[24:31], v[192:199], v[148:151]
	v_mfma_f32_16x16x128_f8f6f4 v[140:143], v[16:23], v[192:199], v[140:143]
	v_mfma_f32_16x16x128_f8f6f4 v[132:135], v[24:31], v[200:207], v[132:135]
	v_mfma_f32_16x16x128_f8f6f4 v[124:127], v[16:23], v[200:207], v[124:127]
	v_mfma_f32_16x16x128_f8f6f4 v[116:119], v[24:31], v[208:215], v[116:119]
	v_mfma_f32_16x16x128_f8f6f4 v[108:111], v[16:23], v[208:215], v[108:111]
	s_setprio 0
	s_setprio 1
	v_mfma_f32_16x16x128_f8f6f4 v[144:147], v[8:15], v[176:183], v[144:147]
	v_mfma_f32_16x16x128_f8f6f4 v[136:139], v[0:7], v[176:183], v[136:139]
	v_mfma_f32_16x16x128_f8f6f4 v[128:131], v[8:15], v[192:199], v[128:131]
	v_mfma_f32_16x16x128_f8f6f4 v[120:123], v[0:7], v[192:199], v[120:123]
	v_mfma_f32_16x16x128_f8f6f4 v[112:115], v[8:15], v[200:207], v[112:115]
	v_mfma_f32_16x16x128_f8f6f4 v[104:107], v[0:7], v[200:207], v[104:107]
	v_mfma_f32_16x16x128_f8f6f4 v[100:103], v[8:15], v[208:215], v[100:103]
	s_barrier
	v_mfma_f32_16x16x128_f8f6f4 v[96:99], v[0:7], v[208:215], v[96:99]
	s_setprio 0
	s_mov_b32 m0, s13
	ds_read_b128 v[192:195], v190 offset:16384
	ds_read_b128 v[196:199], v190 offset:16400
	ds_read_b128 v[200:203], v190 offset:18432
	ds_read_b128 v[204:207], v190 offset:18448
	ds_read_b128 v[208:211], v190 offset:20480
	ds_read_b128 v[212:215], v190 offset:20496
	ds_read_b128 v[216:219], v190 offset:22528
	ds_read_b128 v[220:223], v190 offset:22544
	global_load_lds_dwordx4 v166, s[24:25]
	s_mov_b32 m0, s22
	s_add_u32 s50, s24, 0x58000
	global_load_lds_dwordx4 v170, s[24:25]
	s_addc_u32 s51, s25, 0
	s_mov_b32 m0, s23
	v_mov_b32_e32 v167, v165
	global_load_lds_dwordx4 v166, s[50:51]
	s_mov_b32 m0, s28
	v_mov_b32_e32 v171, v165
	global_load_lds_dwordx4 v170, s[50:51]
	s_waitcnt vmcnt(6)
	s_waitcnt lgkmcnt(0)
	s_barrier
	s_setprio 1
	s_waitcnt lgkmcnt(0)
	v_mfma_f32_16x16x128_f8f6f4 v[92:95], v[24:31], v[192:199], v[92:95]
	v_mfma_f32_16x16x128_f8f6f4 v[88:91], v[16:23], v[192:199], v[88:91]
	s_mov_b32 m0, s3
	v_lshl_add_u64 v[182:183], s[24:25], 0, v[166:167]
	v_mfma_f32_16x16x128_f8f6f4 v[84:87], v[24:31], v[200:207], v[84:87]
	global_load_lds_dwordx4 v164, s[26:27]
	v_mfma_f32_16x16x128_f8f6f4 v[76:79], v[16:23], v[200:207], v[76:79]
	v_mfma_f32_16x16x128_f8f6f4 v[68:71], v[24:31], v[208:215], v[68:71]
	v_mfma_f32_16x16x128_f8f6f4 v[60:63], v[16:23], v[208:215], v[60:63]
	v_mfma_f32_16x16x128_f8f6f4 v[52:55], v[24:31], v[216:223], v[52:55]
	v_mfma_f32_16x16x128_f8f6f4 v[44:47], v[16:23], v[216:223], v[44:47]
	s_mov_b32 m0, s29
	v_lshl_add_u64 v[180:181], s[24:25], 0, v[170:171]
	s_setprio 0
	s_setprio 1
	v_mfma_f32_16x16x128_f8f6f4 v[80:83], v[8:15], v[192:199], v[80:83]
	global_load_lds_dwordx4 v168, s[26:27]
	v_lshl_add_u64 v[178:179], s[26:27], 0, v[164:165]
	v_lshl_add_u64 v[176:177], s[26:27], 0, v[168:169]
	v_mfma_f32_16x16x128_f8f6f4 v[72:75], v[0:7], v[192:199], v[72:75]
	v_mfma_f32_16x16x128_f8f6f4 v[64:67], v[8:15], v[200:207], v[64:67]
	v_mfma_f32_16x16x128_f8f6f4 v[56:59], v[0:7], v[200:207], v[56:59]
	v_mfma_f32_16x16x128_f8f6f4 v[48:51], v[8:15], v[208:215], v[48:51]
	v_mfma_f32_16x16x128_f8f6f4 v[40:43], v[0:7], v[208:215], v[40:43]
	v_mfma_f32_16x16x128_f8f6f4 v[36:39], v[8:15], v[216:223], v[36:39]
	s_barrier
	v_mfma_f32_16x16x128_f8f6f4 v[32:35], v[0:7], v[216:223], v[32:35]
	s_setprio 0
	ds_read_b128 v[0:3], v189 offset:32768
	ds_read_b128 v[4:7], v189 offset:32784
	ds_read_b128 v[8:11], v189 offset:34816
	ds_read_b128 v[12:15], v189 offset:34832
	ds_read_b128 v[16:19], v189 offset:49152
	ds_read_b128 v[20:23], v189 offset:49168
	ds_read_b128 v[24:27], v189 offset:51200
	ds_read_b128 v[28:31], v189 offset:51216
	s_add_u32 s26, s26, 0x58000
	s_addc_u32 s27, s27, 0
	s_mov_b32 m0, s30
	ds_read_b128 v[192:195], v190 offset:32768
	ds_read_b128 v[196:199], v190 offset:32784
	ds_read_b128 v[200:203], v190 offset:34816
	ds_read_b128 v[204:207], v190 offset:34832
	ds_read_b128 v[208:211], v190 offset:36864
	ds_read_b128 v[212:215], v190 offset:36880
	ds_read_b128 v[216:219], v190 offset:38912
	ds_read_b128 v[220:223], v190 offset:38928
	global_load_lds_dwordx4 v164, s[26:27]
	s_mov_b32 m0, s31
	s_nop 0
	global_load_lds_dwordx4 v168, s[26:27]
	s_waitcnt vmcnt(8)
	s_waitcnt lgkmcnt(0)
	s_barrier
	s_setprio 1
	s_waitcnt lgkmcnt(0)
	v_mfma_f32_16x16x128_f8f6f4 v[156:159], v[0:7], v[192:199], v[156:159]
	v_mfma_f32_16x16x128_f8f6f4 v[152:155], v[8:15], v[192:199], v[152:155]
	v_mfma_f32_16x16x128_f8f6f4 v[148:151], v[0:7], v[200:207], v[148:151]
	v_mfma_f32_16x16x128_f8f6f4 v[140:143], v[8:15], v[200:207], v[140:143]
	v_mfma_f32_16x16x128_f8f6f4 v[132:135], v[0:7], v[208:215], v[132:135]
	v_mfma_f32_16x16x128_f8f6f4 v[124:127], v[8:15], v[208:215], v[124:127]
	v_mfma_f32_16x16x128_f8f6f4 v[116:119], v[0:7], v[216:223], v[116:119]
	v_mfma_f32_16x16x128_f8f6f4 v[108:111], v[8:15], v[216:223], v[108:111]
	s_setprio 0
	s_setprio 1
	v_mfma_f32_16x16x128_f8f6f4 v[144:147], v[16:23], v[192:199], v[144:147]
	v_mfma_f32_16x16x128_f8f6f4 v[136:139], v[24:31], v[192:199], v[136:139]
	v_mfma_f32_16x16x128_f8f6f4 v[128:131], v[16:23], v[200:207], v[128:131]
	v_mfma_f32_16x16x128_f8f6f4 v[120:123], v[24:31], v[200:207], v[120:123]
	v_mfma_f32_16x16x128_f8f6f4 v[112:115], v[16:23], v[208:215], v[112:115]
	v_mfma_f32_16x16x128_f8f6f4 v[104:107], v[24:31], v[208:215], v[104:107]
	v_mfma_f32_16x16x128_f8f6f4 v[100:103], v[16:23], v[216:223], v[100:103]
	s_barrier
	v_mfma_f32_16x16x128_f8f6f4 v[96:99], v[24:31], v[216:223], v[96:99]
	s_setprio 0
	s_mov_b32 m0, s35
	v_lshl_add_u64 v[182:183], v[182:183], 0, s[8:9]
	ds_read_b128 v[192:195], v190 offset:49152
	ds_read_b128 v[196:199], v190 offset:49168
	ds_read_b128 v[200:203], v190 offset:51200
	ds_read_b128 v[204:207], v190 offset:51216
	ds_read_b128 v[208:211], v190 offset:53248
	ds_read_b128 v[212:215], v190 offset:53264
	ds_read_b128 v[216:219], v190 offset:55296
	ds_read_b128 v[220:223], v190 offset:55312
	global_load_lds_dwordx4 v[182:183], off
	v_lshl_add_u64 v[180:181], v[180:181], 0, s[8:9]
	s_mov_b32 m0, s36
	s_add_u32 s24, s24, 0x58080
	global_load_lds_dwordx4 v[180:181], off
	s_addc_u32 s25, s25, 0
	s_mov_b32 m0, s39
	v_lshl_add_u64 v[178:179], v[178:179], 0, s[8:9]
	global_load_lds_dwordx4 v166, s[24:25]
	s_mov_b32 m0, s40
	v_lshl_add_u64 v[176:177], v[176:177], 0, s[8:9]
	global_load_lds_dwordx4 v170, s[24:25]
	s_waitcnt vmcnt(6)
	s_waitcnt lgkmcnt(0)
	s_barrier
	s_setprio 1
	s_waitcnt lgkmcnt(0)
	v_mfma_f32_16x16x128_f8f6f4 v[92:95], v[0:7], v[192:199], v[92:95]
	v_mfma_f32_16x16x128_f8f6f4 v[88:91], v[8:15], v[192:199], v[88:91]
	s_mov_b32 m0, s37
	v_mfma_f32_16x16x128_f8f6f4 v[84:87], v[0:7], v[200:207], v[84:87]
	global_load_lds_dwordx4 v[178:179], off
	v_mfma_f32_16x16x128_f8f6f4 v[76:79], v[8:15], v[200:207], v[76:79]
	v_mfma_f32_16x16x128_f8f6f4 v[68:71], v[0:7], v[208:215], v[68:71]
	v_mfma_f32_16x16x128_f8f6f4 v[60:63], v[8:15], v[208:215], v[60:63]
	v_mfma_f32_16x16x128_f8f6f4 v[52:55], v[0:7], v[216:223], v[52:55]
	v_mfma_f32_16x16x128_f8f6f4 v[44:47], v[8:15], v[216:223], v[44:47]
	s_mov_b32 m0, s38
	s_setprio 0
	s_setprio 1
	v_mfma_f32_16x16x128_f8f6f4 v[80:83], v[16:23], v[192:199], v[80:83]
	global_load_lds_dwordx4 v[176:177], off
	v_mfma_f32_16x16x128_f8f6f4 v[72:75], v[24:31], v[192:199], v[72:75]
	v_mfma_f32_16x16x128_f8f6f4 v[64:67], v[16:23], v[200:207], v[64:67]
	v_mfma_f32_16x16x128_f8f6f4 v[56:59], v[24:31], v[200:207], v[56:59]
	v_mfma_f32_16x16x128_f8f6f4 v[48:51], v[16:23], v[208:215], v[48:51]
	v_mfma_f32_16x16x128_f8f6f4 v[40:43], v[24:31], v[208:215], v[40:43]
	v_mfma_f32_16x16x128_f8f6f4 v[36:39], v[16:23], v[216:223], v[36:39]
	s_barrier
	v_mfma_f32_16x16x128_f8f6f4 v[32:35], v[24:31], v[216:223], v[32:35]
	s_nop 0
	s_setprio 0
	s_add_i32 s48, s48, 2
	s_add_u32 s20, s20, 0x100
	s_addc_u32 s21, s21, 0
	s_add_u32 s45, s45, 0x100
	s_addc_u32 s47, s47, 0
	s_cmp_gt_u32 s48, 19
	s_cbranch_scc0 .LBB0_662
	s_nop 15
	s_nop 15
	s_and_b64 vcc, exec, s[10:11]
	s_cbranch_vccz .LBB0_665
	s_barrier

.LBB0_792:
	ds_read_b128 v[144:147], v142
	ds_read_b128 v[148:151], v142 offset:1024
	ds_read_b128 v[152:155], v142 offset:2048
	ds_read_b128 v[156:159], v142 offset:3072
	ds_read_b128 v[164:167], v142 offset:16384
	ds_read_b128 v[168:171], v142 offset:17408
	ds_read_b128 v[172:175], v142 offset:18432
	ds_read_b128 v[176:179], v142 offset:19456
	s_add_u32 s26, s24, 0xfffc0080
	s_addc_u32 s27, s25, -1
	s_cmp_eq_u32 s49, 12
	s_cselect_b32 s29, s13, s27
	s_cselect_b32 s28, s44, s26
	s_cselect_b32 s27, s11, s48
	s_cselect_b32 s26, s45, s47
	s_add_i32 m0, s3, 0xc000
	ds_read_b128 v[180:183], v143
	ds_read_b128 v[188:191], v143 offset:1024
	ds_read_b128 v[192:195], v143 offset:2048
	ds_read_b128 v[196:199], v143 offset:3072
	ds_read_b128 v[200:203], v143 offset:4096
	ds_read_b128 v[204:207], v143 offset:5120
	ds_read_b128 v[208:211], v143 offset:6144
	ds_read_b128 v[212:215], v143 offset:7168
	global_load_lds_dwordx4 v128, s[24:25]
	s_add_i32 m0, s3, 0xe000
	v_mov_b32_e32 v131, v129
	global_load_lds_dwordx4 v130, s[24:25]
	s_waitcnt vmcnt(8)
	s_waitcnt lgkmcnt(0)
	s_barrier
	s_setprio 1
	s_waitcnt lgkmcnt(0)
	v_mfma_f32_16x16x32_bf16 v[124:127], v[144:147], v[180:183], v[124:127]
	v_mfma_f32_16x16x32_bf16 v[120:123], v[152:155], v[180:183], v[120:123]
	v_mfma_f32_16x16x32_bf16 v[116:119], v[144:147], v[192:195], v[116:119]
	v_mfma_f32_16x16x32_bf16 v[112:115], v[152:155], v[192:195], v[112:115]
	v_mfma_f32_16x16x32_bf16 v[100:103], v[144:147], v[200:203], v[100:103]
	v_mfma_f32_16x16x32_bf16 v[96:99], v[152:155], v[200:203], v[96:99]
	v_mfma_f32_16x16x32_bf16 v[84:87], v[144:147], v[208:211], v[84:87]
	v_mfma_f32_16x16x32_bf16 v[80:83], v[152:155], v[208:211], v[80:83]
	v_mfma_f32_16x16x32_bf16 v[124:127], v[148:151], v[188:191], v[124:127]
	v_mfma_f32_16x16x32_bf16 v[120:123], v[156:159], v[188:191], v[120:123]
	v_mfma_f32_16x16x32_bf16 v[116:119], v[148:151], v[196:199], v[116:119]
	v_mfma_f32_16x16x32_bf16 v[112:115], v[156:159], v[196:199], v[112:115]
	v_mfma_f32_16x16x32_bf16 v[100:103], v[148:151], v[204:207], v[100:103]
	v_mfma_f32_16x16x32_bf16 v[96:99], v[156:159], v[204:207], v[96:99]
	v_mfma_f32_16x16x32_bf16 v[84:87], v[148:151], v[212:215], v[84:87]
	v_mfma_f32_16x16x32_bf16 v[80:83], v[156:159], v[212:215], v[80:83]
	s_setprio 0
	s_setprio 1
	v_mfma_f32_16x16x32_bf16 v[108:111], v[164:167], v[180:183], v[108:111]
	v_mfma_f32_16x16x32_bf16 v[104:107], v[172:175], v[180:183], v[104:107]
	v_mfma_f32_16x16x32_bf16 v[92:95], v[164:167], v[192:195], v[92:95]
	v_mfma_f32_16x16x32_bf16 v[88:91], v[172:175], v[192:195], v[88:91]
	v_mfma_f32_16x16x32_bf16 v[76:79], v[164:167], v[200:203], v[76:79]
	v_mfma_f32_16x16x32_bf16 v[72:75], v[172:175], v[200:203], v[72:75]
	v_mfma_f32_16x16x32_bf16 v[68:71], v[164:167], v[208:211], v[68:71]
	v_mfma_f32_16x16x32_bf16 v[64:67], v[172:175], v[208:211], v[64:67]
	v_mfma_f32_16x16x32_bf16 v[108:111], v[168:171], v[188:191], v[108:111]
	v_mfma_f32_16x16x32_bf16 v[104:107], v[176:179], v[188:191], v[104:107]
	v_mfma_f32_16x16x32_bf16 v[92:95], v[168:171], v[196:199], v[92:95]
	v_mfma_f32_16x16x32_bf16 v[88:91], v[176:179], v[196:199], v[88:91]
	v_mfma_f32_16x16x32_bf16 v[76:79], v[168:171], v[204:207], v[76:79]
	v_mfma_f32_16x16x32_bf16 v[72:75], v[176:179], v[204:207], v[72:75]
	v_mfma_f32_16x16x32_bf16 v[68:71], v[168:171], v[212:215], v[68:71]
	s_barrier
	v_mfma_f32_16x16x32_bf16 v[64:67], v[176:179], v[212:215], v[64:67]
	s_setprio 0
	s_mov_b32 m0, s15
	ds_read_b128 v[180:183], v143 offset:16384
	ds_read_b128 v[188:191], v143 offset:17408
	ds_read_b128 v[192:195], v143 offset:18432
	ds_read_b128 v[196:199], v143 offset:19456
	ds_read_b128 v[200:203], v143 offset:20480
	ds_read_b128 v[204:207], v143 offset:21504
	ds_read_b128 v[208:211], v143 offset:22528
	ds_read_b128 v[212:215], v143 offset:23552
	global_load_lds_dwordx4 v138, s[26:27]
	s_mov_b32 m0, s22
	s_add_u32 s50, s26, 0x40000
	global_load_lds_dwordx4 v132, s[26:27]
	s_addc_u32 s51, s27, 0
	s_mov_b32 m0, s23
	v_mov_b32_e32 v139, v129
	global_load_lds_dwordx4 v138, s[50:51]
	s_mov_b32 m0, s30
	v_mov_b32_e32 v133, v129
	global_load_lds_dwordx4 v132, s[50:51]
	s_waitcnt vmcnt(6)
	s_waitcnt lgkmcnt(0)
	s_barrier
	s_setprio 1
	s_waitcnt lgkmcnt(0)
	v_mfma_f32_16x16x32_bf16 v[60:63], v[144:147], v[180:183], v[60:63]
	v_mfma_f32_16x16x32_bf16 v[56:59], v[152:155], v[180:183], v[56:59]
	s_mov_b32 m0, s3
	v_lshl_add_u64 v[216:217], s[26:27], 0, v[138:139]
	v_mfma_f32_16x16x32_bf16 v[52:55], v[144:147], v[192:195], v[52:55]
	global_load_lds_dwordx4 v128, s[28:29]
	v_mfma_f32_16x16x32_bf16 v[48:51], v[152:155], v[192:195], v[48:51]
	v_mfma_f32_16x16x32_bf16 v[36:39], v[144:147], v[200:203], v[36:39]
	v_mfma_f32_16x16x32_bf16 v[32:35], v[152:155], v[200:203], v[32:35]
	v_mfma_f32_16x16x32_bf16 v[20:23], v[144:147], v[208:211], v[20:23]
	v_mfma_f32_16x16x32_bf16 v[16:19], v[152:155], v[208:211], v[16:19]
	v_mfma_f32_16x16x32_bf16 v[60:63], v[148:151], v[188:191], v[60:63]
	v_mfma_f32_16x16x32_bf16 v[56:59], v[156:159], v[188:191], v[56:59]
	v_mfma_f32_16x16x32_bf16 v[52:55], v[148:151], v[196:199], v[52:55]
	v_mfma_f32_16x16x32_bf16 v[48:51], v[156:159], v[196:199], v[48:51]
	v_mfma_f32_16x16x32_bf16 v[36:39], v[148:151], v[204:207], v[36:39]
	v_mfma_f32_16x16x32_bf16 v[32:35], v[156:159], v[204:207], v[32:35]
	v_mfma_f32_16x16x32_bf16 v[20:23], v[148:151], v[212:215], v[20:23]
	v_mfma_f32_16x16x32_bf16 v[16:19], v[156:159], v[212:215], v[16:19]
	s_mov_b32 m0, s31
	v_lshl_add_u64 v[218:219], s[26:27], 0, v[132:133]
	s_setprio 0
	s_setprio 1
	v_mfma_f32_16x16x32_bf16 v[44:47], v[164:167], v[180:183], v[44:47]
	global_load_lds_dwordx4 v130, s[28:29]
	v_lshl_add_u64 v[220:221], s[28:29], 0, v[128:129]
	v_lshl_add_u64 v[222:223], s[28:29], 0, v[130:131]
	v_mfma_f32_16x16x32_bf16 v[40:43], v[172:175], v[180:183], v[40:43]
	v_mfma_f32_16x16x32_bf16 v[28:31], v[164:167], v[192:195], v[28:31]
	v_mfma_f32_16x16x32_bf16 v[24:27], v[172:175], v[192:195], v[24:27]
	v_mfma_f32_16x16x32_bf16 v[12:15], v[164:167], v[200:203], v[12:15]
	v_mfma_f32_16x16x32_bf16 v[8:11], v[172:175], v[200:203], v[8:11]
	v_mfma_f32_16x16x32_bf16 v[4:7], v[164:167], v[208:211], v[4:7]
	v_mfma_f32_16x16x32_bf16 v[0:3], v[172:175], v[208:211], v[0:3]
	v_mfma_f32_16x16x32_bf16 v[44:47], v[168:171], v[188:191], v[44:47]
	v_mfma_f32_16x16x32_bf16 v[40:43], v[176:179], v[188:191], v[40:43]
	v_mfma_f32_16x16x32_bf16 v[28:31], v[168:171], v[196:199], v[28:31]
	v_mfma_f32_16x16x32_bf16 v[24:27], v[176:179], v[196:199], v[24:27]
	v_mfma_f32_16x16x32_bf16 v[12:15], v[168:171], v[204:207], v[12:15]
	v_mfma_f32_16x16x32_bf16 v[8:11], v[176:179], v[204:207], v[8:11]
	v_mfma_f32_16x16x32_bf16 v[4:7], v[168:171], v[212:215], v[4:7]
	s_barrier
	v_mfma_f32_16x16x32_bf16 v[0:3], v[176:179], v[212:215], v[0:3]
	s_setprio 0
	ds_read_b128 v[144:147], v142 offset:32768
	ds_read_b128 v[148:151], v142 offset:33792
	ds_read_b128 v[152:155], v142 offset:34816
	ds_read_b128 v[156:159], v142 offset:35840
	ds_read_b128 v[164:167], v142 offset:49152
	ds_read_b128 v[168:171], v142 offset:50176
	ds_read_b128 v[172:175], v142 offset:51200
	ds_read_b128 v[176:179], v142 offset:52224
	s_add_u32 s28, s28, 0x40000
	s_addc_u32 s29, s29, 0
	s_mov_b32 m0, s34
	ds_read_b128 v[180:183], v143 offset:32768
	ds_read_b128 v[188:191], v143 offset:33792
	ds_read_b128 v[192:195], v143 offset:34816
	ds_read_b128 v[196:199], v143 offset:35840
	ds_read_b128 v[200:203], v143 offset:36864
	ds_read_b128 v[204:207], v143 offset:37888
	ds_read_b128 v[208:211], v143 offset:38912
	ds_read_b128 v[212:215], v143 offset:39936
	global_load_lds_dwordx4 v128, s[28:29]
	s_mov_b32 m0, s35
	s_nop 0
	global_load_lds_dwordx4 v130, s[28:29]
	s_waitcnt vmcnt(8)
	s_waitcnt lgkmcnt(0)
	s_barrier
	s_setprio 1
	s_waitcnt lgkmcnt(0)
	v_mfma_f32_16x16x32_bf16 v[124:127], v[144:147], v[180:183], v[124:127]
	v_mfma_f32_16x16x32_bf16 v[120:123], v[152:155], v[180:183], v[120:123]
	v_mfma_f32_16x16x32_bf16 v[116:119], v[144:147], v[192:195], v[116:119]
	v_mfma_f32_16x16x32_bf16 v[112:115], v[152:155], v[192:195], v[112:115]
	v_mfma_f32_16x16x32_bf16 v[100:103], v[144:147], v[200:203], v[100:103]
	v_mfma_f32_16x16x32_bf16 v[96:99], v[152:155], v[200:203], v[96:99]
	v_mfma_f32_16x16x32_bf16 v[84:87], v[144:147], v[208:211], v[84:87]
	v_mfma_f32_16x16x32_bf16 v[80:83], v[152:155], v[208:211], v[80:83]
	v_mfma_f32_16x16x32_bf16 v[124:127], v[148:151], v[188:191], v[124:127]
	v_mfma_f32_16x16x32_bf16 v[120:123], v[156:159], v[188:191], v[120:123]
	v_mfma_f32_16x16x32_bf16 v[116:119], v[148:151], v[196:199], v[116:119]
	v_mfma_f32_16x16x32_bf16 v[112:115], v[156:159], v[196:199], v[112:115]
	v_mfma_f32_16x16x32_bf16 v[100:103], v[148:151], v[204:207], v[100:103]
	v_mfma_f32_16x16x32_bf16 v[96:99], v[156:159], v[204:207], v[96:99]
	v_mfma_f32_16x16x32_bf16 v[84:87], v[148:151], v[212:215], v[84:87]
	v_mfma_f32_16x16x32_bf16 v[80:83], v[156:159], v[212:215], v[80:83]
	s_setprio 0
	s_setprio 1
	v_mfma_f32_16x16x32_bf16 v[108:111], v[164:167], v[180:183], v[108:111]
	v_mfma_f32_16x16x32_bf16 v[104:107], v[172:175], v[180:183], v[104:107]
	v_mfma_f32_16x16x32_bf16 v[92:95], v[164:167], v[192:195], v[92:95]
	v_mfma_f32_16x16x32_bf16 v[88:91], v[172:175], v[192:195], v[88:91]
	v_mfma_f32_16x16x32_bf16 v[76:79], v[164:167], v[200:203], v[76:79]
	v_mfma_f32_16x16x32_bf16 v[72:75], v[172:175], v[200:203], v[72:75]
	v_mfma_f32_16x16x32_bf16 v[68:71], v[164:167], v[208:211], v[68:71]
	v_mfma_f32_16x16x32_bf16 v[64:67], v[172:175], v[208:211], v[64:67]
	v_mfma_f32_16x16x32_bf16 v[108:111], v[168:171], v[188:191], v[108:111]
	v_mfma_f32_16x16x32_bf16 v[104:107], v[176:179], v[188:191], v[104:107]
	v_mfma_f32_16x16x32_bf16 v[92:95], v[168:171], v[196:199], v[92:95]
	v_mfma_f32_16x16x32_bf16 v[88:91], v[176:179], v[196:199], v[88:91]
	v_mfma_f32_16x16x32_bf16 v[76:79], v[168:171], v[204:207], v[76:79]
	v_mfma_f32_16x16x32_bf16 v[72:75], v[176:179], v[204:207], v[72:75]
	v_mfma_f32_16x16x32_bf16 v[68:71], v[168:171], v[212:215], v[68:71]
	s_barrier
	v_mfma_f32_16x16x32_bf16 v[64:67], v[176:179], v[212:215], v[64:67]
	s_setprio 0
	s_mov_b32 m0, s37
	v_lshl_add_u64 v[216:217], v[216:217], 0, s[6:7]
	ds_read_b128 v[180:183], v143 offset:49152
	ds_read_b128 v[188:191], v143 offset:50176
	ds_read_b128 v[192:195], v143 offset:51200
	ds_read_b128 v[196:199], v143 offset:52224
	ds_read_b128 v[200:203], v143 offset:53248
	ds_read_b128 v[204:207], v143 offset:54272
	ds_read_b128 v[208:211], v143 offset:55296
	ds_read_b128 v[212:215], v143 offset:56320
	global_load_lds_dwordx4 v[216:217], off
	v_lshl_add_u64 v[216:217], v[218:219], 0, s[6:7]
	s_mov_b32 m0, s38
	s_add_u32 s26, s26, 0x40080
	global_load_lds_dwordx4 v[216:217], off
	s_addc_u32 s27, s27, 0
	s_mov_b32 m0, s41
	v_lshl_add_u64 v[216:217], v[220:221], 0, s[6:7]
	global_load_lds_dwordx4 v138, s[26:27]
	s_mov_b32 m0, s42
	s_nop 0
	global_load_lds_dwordx4 v132, s[26:27]
	s_waitcnt vmcnt(6)
	s_waitcnt lgkmcnt(0)
	s_barrier
	s_setprio 1
	s_waitcnt lgkmcnt(0)
	v_mfma_f32_16x16x32_bf16 v[60:63], v[144:147], v[180:183], v[60:63]
	v_mfma_f32_16x16x32_bf16 v[56:59], v[152:155], v[180:183], v[56:59]
	s_mov_b32 m0, s39
	v_mfma_f32_16x16x32_bf16 v[52:55], v[144:147], v[192:195], v[52:55]
	global_load_lds_dwordx4 v[216:217], off
	v_mfma_f32_16x16x32_bf16 v[48:51], v[152:155], v[192:195], v[48:51]
	v_mfma_f32_16x16x32_bf16 v[36:39], v[144:147], v[200:203], v[36:39]
	v_mfma_f32_16x16x32_bf16 v[32:35], v[152:155], v[200:203], v[32:35]
	v_mfma_f32_16x16x32_bf16 v[20:23], v[144:147], v[208:211], v[20:23]
	v_mfma_f32_16x16x32_bf16 v[16:19], v[152:155], v[208:211], v[16:19]
	v_mfma_f32_16x16x32_bf16 v[60:63], v[148:151], v[188:191], v[60:63]
	v_mfma_f32_16x16x32_bf16 v[56:59], v[156:159], v[188:191], v[56:59]
	v_mfma_f32_16x16x32_bf16 v[52:55], v[148:151], v[196:199], v[52:55]
	v_mfma_f32_16x16x32_bf16 v[48:51], v[156:159], v[196:199], v[48:51]
	v_mfma_f32_16x16x32_bf16 v[36:39], v[148:151], v[204:207], v[36:39]
	v_mfma_f32_16x16x32_bf16 v[32:35], v[156:159], v[204:207], v[32:35]
	v_mfma_f32_16x16x32_bf16 v[20:23], v[148:151], v[212:215], v[20:23]
	v_mfma_f32_16x16x32_bf16 v[16:19], v[156:159], v[212:215], v[16:19]
	v_lshl_add_u64 v[216:217], v[222:223], 0, s[6:7]
	s_mov_b32 m0, s40
	s_setprio 0
	s_setprio 1
	v_mfma_f32_16x16x32_bf16 v[44:47], v[164:167], v[180:183], v[44:47]
	global_load_lds_dwordx4 v[216:217], off
	v_mfma_f32_16x16x32_bf16 v[40:43], v[172:175], v[180:183], v[40:43]
	v_mfma_f32_16x16x32_bf16 v[28:31], v[164:167], v[192:195], v[28:31]
	v_mfma_f32_16x16x32_bf16 v[24:27], v[172:175], v[192:195], v[24:27]
	v_mfma_f32_16x16x32_bf16 v[12:15], v[164:167], v[200:203], v[12:15]
	v_mfma_f32_16x16x32_bf16 v[8:11], v[172:175], v[200:203], v[8:11]
	v_mfma_f32_16x16x32_bf16 v[4:7], v[164:167], v[208:211], v[4:7]
	v_mfma_f32_16x16x32_bf16 v[0:3], v[172:175], v[208:211], v[0:3]
	v_mfma_f32_16x16x32_bf16 v[44:47], v[168:171], v[188:191], v[44:47]
	v_mfma_f32_16x16x32_bf16 v[40:43], v[176:179], v[188:191], v[40:43]
	v_mfma_f32_16x16x32_bf16 v[28:31], v[168:171], v[196:199], v[28:31]
	v_mfma_f32_16x16x32_bf16 v[24:27], v[176:179], v[196:199], v[24:27]
	v_mfma_f32_16x16x32_bf16 v[12:15], v[168:171], v[204:207], v[12:15]
	v_mfma_f32_16x16x32_bf16 v[8:11], v[176:179], v[204:207], v[8:11]
	v_mfma_f32_16x16x32_bf16 v[4:7], v[168:171], v[212:215], v[4:7]
	s_barrier
	v_mfma_f32_16x16x32_bf16 v[0:3], v[176:179], v[212:215], v[0:3]
	s_nop 0
	s_setprio 0
	s_add_i32 s49, s49, 2
	s_add_u32 s24, s24, 0x100
	s_addc_u32 s25, s25, 0
	s_add_u32 s47, s47, 0x100
	s_addc_u32 s48, s48, 0
	s_cmp_gt_u32 s49, 13
	s_cbranch_scc0 .LBB0_792
	s_and_b64 vcc, exec, s[8:9]
	s_cbranch_vccz .LBB0_795
	s_barrier

.LBB0_993:
	ds_read_b128 v[144:147], v142
	ds_read_b128 v[148:151], v142 offset:1024
	ds_read_b128 v[152:155], v142 offset:2048
	ds_read_b128 v[156:159], v142 offset:3072
	ds_read_b128 v[164:167], v142 offset:16384
	ds_read_b128 v[168:171], v142 offset:17408
	ds_read_b128 v[172:175], v142 offset:18432
	ds_read_b128 v[176:179], v142 offset:19456
	s_add_u32 s28, s26, 0xfffc0080
	s_addc_u32 s29, s27, -1
	s_cmp_eq_u32 s54, 12
	s_cselect_b32 s31, s17, s29
	s_cselect_b32 s30, s50, s28
	s_cselect_b32 s29, s15, s53
	s_cselect_b32 s28, s51, s52
	s_add_i32 m0, s3, 0xc000
	ds_read_b128 v[180:183], v143
	ds_read_b128 v[188:191], v143 offset:1024
	ds_read_b128 v[192:195], v143 offset:2048
	ds_read_b128 v[196:199], v143 offset:3072
	ds_read_b128 v[200:203], v143 offset:4096
	ds_read_b128 v[204:207], v143 offset:5120
	ds_read_b128 v[208:211], v143 offset:6144
	ds_read_b128 v[212:215], v143 offset:7168
	global_load_lds_dwordx4 v128, s[26:27]
	s_add_i32 m0, s3, 0xe000
	v_mov_b32_e32 v131, v129
	global_load_lds_dwordx4 v130, s[26:27]
	s_waitcnt vmcnt(8)
	s_waitcnt lgkmcnt(0)
	s_barrier
	s_setprio 1
	s_waitcnt lgkmcnt(0)
	v_mfma_f32_16x16x32_bf16 v[124:127], v[144:147], v[180:183], v[124:127]
	v_mfma_f32_16x16x32_bf16 v[120:123], v[152:155], v[180:183], v[120:123]
	v_mfma_f32_16x16x32_bf16 v[116:119], v[144:147], v[192:195], v[116:119]
	v_mfma_f32_16x16x32_bf16 v[112:115], v[152:155], v[192:195], v[112:115]
	v_mfma_f32_16x16x32_bf16 v[100:103], v[144:147], v[200:203], v[100:103]
	v_mfma_f32_16x16x32_bf16 v[96:99], v[152:155], v[200:203], v[96:99]
	v_mfma_f32_16x16x32_bf16 v[84:87], v[144:147], v[208:211], v[84:87]
	v_mfma_f32_16x16x32_bf16 v[80:83], v[152:155], v[208:211], v[80:83]
	v_mfma_f32_16x16x32_bf16 v[124:127], v[148:151], v[188:191], v[124:127]
	v_mfma_f32_16x16x32_bf16 v[120:123], v[156:159], v[188:191], v[120:123]
	v_mfma_f32_16x16x32_bf16 v[116:119], v[148:151], v[196:199], v[116:119]
	v_mfma_f32_16x16x32_bf16 v[112:115], v[156:159], v[196:199], v[112:115]
	v_mfma_f32_16x16x32_bf16 v[100:103], v[148:151], v[204:207], v[100:103]
	v_mfma_f32_16x16x32_bf16 v[96:99], v[156:159], v[204:207], v[96:99]
	v_mfma_f32_16x16x32_bf16 v[84:87], v[148:151], v[212:215], v[84:87]
	v_mfma_f32_16x16x32_bf16 v[80:83], v[156:159], v[212:215], v[80:83]
	s_setprio 0
	s_setprio 1
	v_mfma_f32_16x16x32_bf16 v[108:111], v[164:167], v[180:183], v[108:111]
	v_mfma_f32_16x16x32_bf16 v[104:107], v[172:175], v[180:183], v[104:107]
	v_mfma_f32_16x16x32_bf16 v[92:95], v[164:167], v[192:195], v[92:95]
	v_mfma_f32_16x16x32_bf16 v[88:91], v[172:175], v[192:195], v[88:91]
	v_mfma_f32_16x16x32_bf16 v[76:79], v[164:167], v[200:203], v[76:79]
	v_mfma_f32_16x16x32_bf16 v[72:75], v[172:175], v[200:203], v[72:75]
	v_mfma_f32_16x16x32_bf16 v[68:71], v[164:167], v[208:211], v[68:71]
	v_mfma_f32_16x16x32_bf16 v[64:67], v[172:175], v[208:211], v[64:67]
	v_mfma_f32_16x16x32_bf16 v[108:111], v[168:171], v[188:191], v[108:111]
	v_mfma_f32_16x16x32_bf16 v[104:107], v[176:179], v[188:191], v[104:107]
	v_mfma_f32_16x16x32_bf16 v[92:95], v[168:171], v[196:199], v[92:95]
	v_mfma_f32_16x16x32_bf16 v[88:91], v[176:179], v[196:199], v[88:91]
	v_mfma_f32_16x16x32_bf16 v[76:79], v[168:171], v[204:207], v[76:79]
	v_mfma_f32_16x16x32_bf16 v[72:75], v[176:179], v[204:207], v[72:75]
	v_mfma_f32_16x16x32_bf16 v[68:71], v[168:171], v[212:215], v[68:71]
	s_barrier
	v_mfma_f32_16x16x32_bf16 v[64:67], v[176:179], v[212:215], v[64:67]
	s_setprio 0
	s_mov_b32 m0, s19
	ds_read_b128 v[180:183], v143 offset:16384
	ds_read_b128 v[188:191], v143 offset:17408
	ds_read_b128 v[192:195], v143 offset:18432
	ds_read_b128 v[196:199], v143 offset:19456
	ds_read_b128 v[200:203], v143 offset:20480
	ds_read_b128 v[204:207], v143 offset:21504
	ds_read_b128 v[208:211], v143 offset:22528
	ds_read_b128 v[212:215], v143 offset:23552
	global_load_lds_dwordx4 v138, s[28:29]
	s_mov_b32 m0, s22
	s_add_u32 s62, s28, 0x40000
	global_load_lds_dwordx4 v132, s[28:29]
	s_addc_u32 s63, s29, 0
	s_mov_b32 m0, s23
	v_mov_b32_e32 v139, v129
	global_load_lds_dwordx4 v138, s[62:63]
	s_mov_b32 m0, s34
	v_mov_b32_e32 v133, v129
	global_load_lds_dwordx4 v132, s[62:63]
	s_waitcnt vmcnt(6)
	s_waitcnt lgkmcnt(0)
	s_barrier
	s_setprio 1
	s_waitcnt lgkmcnt(0)
	v_mfma_f32_16x16x32_bf16 v[60:63], v[144:147], v[180:183], v[60:63]
	v_mfma_f32_16x16x32_bf16 v[56:59], v[152:155], v[180:183], v[56:59]
	s_mov_b32 m0, s3
	v_lshl_add_u64 v[216:217], s[28:29], 0, v[138:139]
	v_mfma_f32_16x16x32_bf16 v[52:55], v[144:147], v[192:195], v[52:55]
	global_load_lds_dwordx4 v128, s[30:31]
	v_mfma_f32_16x16x32_bf16 v[48:51], v[152:155], v[192:195], v[48:51]
	v_mfma_f32_16x16x32_bf16 v[36:39], v[144:147], v[200:203], v[36:39]
	v_mfma_f32_16x16x32_bf16 v[32:35], v[152:155], v[200:203], v[32:35]
	v_mfma_f32_16x16x32_bf16 v[20:23], v[144:147], v[208:211], v[20:23]
	v_mfma_f32_16x16x32_bf16 v[16:19], v[152:155], v[208:211], v[16:19]
	v_mfma_f32_16x16x32_bf16 v[60:63], v[148:151], v[188:191], v[60:63]
	v_mfma_f32_16x16x32_bf16 v[56:59], v[156:159], v[188:191], v[56:59]
	v_mfma_f32_16x16x32_bf16 v[52:55], v[148:151], v[196:199], v[52:55]
	v_mfma_f32_16x16x32_bf16 v[48:51], v[156:159], v[196:199], v[48:51]
	v_mfma_f32_16x16x32_bf16 v[36:39], v[148:151], v[204:207], v[36:39]
	v_mfma_f32_16x16x32_bf16 v[32:35], v[156:159], v[204:207], v[32:35]
	v_mfma_f32_16x16x32_bf16 v[20:23], v[148:151], v[212:215], v[20:23]
	v_mfma_f32_16x16x32_bf16 v[16:19], v[156:159], v[212:215], v[16:19]
	s_mov_b32 m0, s35
	v_lshl_add_u64 v[218:219], s[28:29], 0, v[132:133]
	s_setprio 0
	s_setprio 1
	v_mfma_f32_16x16x32_bf16 v[44:47], v[164:167], v[180:183], v[44:47]
	global_load_lds_dwordx4 v130, s[30:31]
	v_lshl_add_u64 v[220:221], s[30:31], 0, v[128:129]
	v_lshl_add_u64 v[222:223], s[30:31], 0, v[130:131]
	v_mfma_f32_16x16x32_bf16 v[40:43], v[172:175], v[180:183], v[40:43]
	v_mfma_f32_16x16x32_bf16 v[28:31], v[164:167], v[192:195], v[28:31]
	v_mfma_f32_16x16x32_bf16 v[24:27], v[172:175], v[192:195], v[24:27]
	v_mfma_f32_16x16x32_bf16 v[12:15], v[164:167], v[200:203], v[12:15]
	v_mfma_f32_16x16x32_bf16 v[8:11], v[172:175], v[200:203], v[8:11]
	v_mfma_f32_16x16x32_bf16 v[4:7], v[164:167], v[208:211], v[4:7]
	v_mfma_f32_16x16x32_bf16 v[0:3], v[172:175], v[208:211], v[0:3]
	v_mfma_f32_16x16x32_bf16 v[44:47], v[168:171], v[188:191], v[44:47]
	v_mfma_f32_16x16x32_bf16 v[40:43], v[176:179], v[188:191], v[40:43]
	v_mfma_f32_16x16x32_bf16 v[28:31], v[168:171], v[196:199], v[28:31]
	v_mfma_f32_16x16x32_bf16 v[24:27], v[176:179], v[196:199], v[24:27]
	v_mfma_f32_16x16x32_bf16 v[12:15], v[168:171], v[204:207], v[12:15]
	v_mfma_f32_16x16x32_bf16 v[8:11], v[176:179], v[204:207], v[8:11]
	v_mfma_f32_16x16x32_bf16 v[4:7], v[168:171], v[212:215], v[4:7]
	s_barrier
	v_mfma_f32_16x16x32_bf16 v[0:3], v[176:179], v[212:215], v[0:3]
	s_setprio 0
	ds_read_b128 v[144:147], v142 offset:32768
	ds_read_b128 v[148:151], v142 offset:33792
	ds_read_b128 v[152:155], v142 offset:34816
	ds_read_b128 v[156:159], v142 offset:35840
	ds_read_b128 v[164:167], v142 offset:49152
	ds_read_b128 v[168:171], v142 offset:50176
	ds_read_b128 v[172:175], v142 offset:51200
	ds_read_b128 v[176:179], v142 offset:52224
	s_add_u32 s30, s30, 0x40000
	s_addc_u32 s31, s31, 0
	s_mov_b32 m0, s36
	ds_read_b128 v[180:183], v143 offset:32768
	ds_read_b128 v[188:191], v143 offset:33792
	ds_read_b128 v[192:195], v143 offset:34816
	ds_read_b128 v[196:199], v143 offset:35840
	ds_read_b128 v[200:203], v143 offset:36864
	ds_read_b128 v[204:207], v143 offset:37888
	ds_read_b128 v[208:211], v143 offset:38912
	ds_read_b128 v[212:215], v143 offset:39936
	global_load_lds_dwordx4 v128, s[30:31]
	s_mov_b32 m0, s37
	s_nop 0
	global_load_lds_dwordx4 v130, s[30:31]
	s_waitcnt vmcnt(8)
	s_waitcnt lgkmcnt(0)
	s_barrier
	s_setprio 1
	s_waitcnt lgkmcnt(0)
	v_mfma_f32_16x16x32_bf16 v[124:127], v[144:147], v[180:183], v[124:127]
	v_mfma_f32_16x16x32_bf16 v[120:123], v[152:155], v[180:183], v[120:123]
	v_mfma_f32_16x16x32_bf16 v[116:119], v[144:147], v[192:195], v[116:119]
	v_mfma_f32_16x16x32_bf16 v[112:115], v[152:155], v[192:195], v[112:115]
	v_mfma_f32_16x16x32_bf16 v[100:103], v[144:147], v[200:203], v[100:103]
	v_mfma_f32_16x16x32_bf16 v[96:99], v[152:155], v[200:203], v[96:99]
	v_mfma_f32_16x16x32_bf16 v[84:87], v[144:147], v[208:211], v[84:87]
	v_mfma_f32_16x16x32_bf16 v[80:83], v[152:155], v[208:211], v[80:83]
	v_mfma_f32_16x16x32_bf16 v[124:127], v[148:151], v[188:191], v[124:127]
	v_mfma_f32_16x16x32_bf16 v[120:123], v[156:159], v[188:191], v[120:123]
	v_mfma_f32_16x16x32_bf16 v[116:119], v[148:151], v[196:199], v[116:119]
	v_mfma_f32_16x16x32_bf16 v[112:115], v[156:159], v[196:199], v[112:115]
	v_mfma_f32_16x16x32_bf16 v[100:103], v[148:151], v[204:207], v[100:103]
	v_mfma_f32_16x16x32_bf16 v[96:99], v[156:159], v[204:207], v[96:99]
	v_mfma_f32_16x16x32_bf16 v[84:87], v[148:151], v[212:215], v[84:87]
	v_mfma_f32_16x16x32_bf16 v[80:83], v[156:159], v[212:215], v[80:83]
	s_setprio 0
	s_setprio 1
	v_mfma_f32_16x16x32_bf16 v[108:111], v[164:167], v[180:183], v[108:111]
	v_mfma_f32_16x16x32_bf16 v[104:107], v[172:175], v[180:183], v[104:107]
	v_mfma_f32_16x16x32_bf16 v[92:95], v[164:167], v[192:195], v[92:95]
	v_mfma_f32_16x16x32_bf16 v[88:91], v[172:175], v[192:195], v[88:91]
	v_mfma_f32_16x16x32_bf16 v[76:79], v[164:167], v[200:203], v[76:79]
	v_mfma_f32_16x16x32_bf16 v[72:75], v[172:175], v[200:203], v[72:75]
	v_mfma_f32_16x16x32_bf16 v[68:71], v[164:167], v[208:211], v[68:71]
	v_mfma_f32_16x16x32_bf16 v[64:67], v[172:175], v[208:211], v[64:67]
	v_mfma_f32_16x16x32_bf16 v[108:111], v[168:171], v[188:191], v[108:111]
	v_mfma_f32_16x16x32_bf16 v[104:107], v[176:179], v[188:191], v[104:107]
	v_mfma_f32_16x16x32_bf16 v[92:95], v[168:171], v[196:199], v[92:95]
	v_mfma_f32_16x16x32_bf16 v[88:91], v[176:179], v[196:199], v[88:91]
	v_mfma_f32_16x16x32_bf16 v[76:79], v[168:171], v[204:207], v[76:79]
	v_mfma_f32_16x16x32_bf16 v[72:75], v[176:179], v[204:207], v[72:75]
	v_mfma_f32_16x16x32_bf16 v[68:71], v[168:171], v[212:215], v[68:71]
	s_barrier
	v_mfma_f32_16x16x32_bf16 v[64:67], v[176:179], v[212:215], v[64:67]
	s_setprio 0
	s_mov_b32 m0, s39
	v_lshl_add_u64 v[216:217], v[216:217], 0, s[6:7]
	ds_read_b128 v[180:183], v143 offset:49152
	ds_read_b128 v[188:191], v143 offset:50176
	ds_read_b128 v[192:195], v143 offset:51200
	ds_read_b128 v[196:199], v143 offset:52224
	ds_read_b128 v[200:203], v143 offset:53248
	ds_read_b128 v[204:207], v143 offset:54272
	ds_read_b128 v[208:211], v143 offset:55296
	ds_read_b128 v[212:215], v143 offset:56320
	global_load_lds_dwordx4 v[216:217], off
	v_lshl_add_u64 v[216:217], v[218:219], 0, s[6:7]
	s_mov_b32 m0, s40
	s_add_u32 s28, s28, 0x40080
	global_load_lds_dwordx4 v[216:217], off
	s_addc_u32 s29, s29, 0
	s_mov_b32 m0, s43
	v_lshl_add_u64 v[216:217], v[220:221], 0, s[6:7]
	global_load_lds_dwordx4 v138, s[28:29]
	s_mov_b32 m0, s44
	s_nop 0
	global_load_lds_dwordx4 v132, s[28:29]
	s_waitcnt vmcnt(6)
	s_waitcnt lgkmcnt(0)
	s_barrier
	s_setprio 1
	s_waitcnt lgkmcnt(0)
	v_mfma_f32_16x16x32_bf16 v[60:63], v[144:147], v[180:183], v[60:63]
	v_mfma_f32_16x16x32_bf16 v[56:59], v[152:155], v[180:183], v[56:59]
	s_mov_b32 m0, s41
	v_mfma_f32_16x16x32_bf16 v[52:55], v[144:147], v[192:195], v[52:55]
	global_load_lds_dwordx4 v[216:217], off
	v_mfma_f32_16x16x32_bf16 v[48:51], v[152:155], v[192:195], v[48:51]
	v_mfma_f32_16x16x32_bf16 v[36:39], v[144:147], v[200:203], v[36:39]
	v_mfma_f32_16x16x32_bf16 v[32:35], v[152:155], v[200:203], v[32:35]
	v_mfma_f32_16x16x32_bf16 v[20:23], v[144:147], v[208:211], v[20:23]
	v_mfma_f32_16x16x32_bf16 v[16:19], v[152:155], v[208:211], v[16:19]
	v_mfma_f32_16x16x32_bf16 v[60:63], v[148:151], v[188:191], v[60:63]
	v_mfma_f32_16x16x32_bf16 v[56:59], v[156:159], v[188:191], v[56:59]
	v_mfma_f32_16x16x32_bf16 v[52:55], v[148:151], v[196:199], v[52:55]
	v_mfma_f32_16x16x32_bf16 v[48:51], v[156:159], v[196:199], v[48:51]
	v_mfma_f32_16x16x32_bf16 v[36:39], v[148:151], v[204:207], v[36:39]
	v_mfma_f32_16x16x32_bf16 v[32:35], v[156:159], v[204:207], v[32:35]
	v_mfma_f32_16x16x32_bf16 v[20:23], v[148:151], v[212:215], v[20:23]
	v_mfma_f32_16x16x32_bf16 v[16:19], v[156:159], v[212:215], v[16:19]
	v_lshl_add_u64 v[216:217], v[222:223], 0, s[6:7]
	s_mov_b32 m0, s42
	s_setprio 0
	s_setprio 1
	v_mfma_f32_16x16x32_bf16 v[44:47], v[164:167], v[180:183], v[44:47]
	global_load_lds_dwordx4 v[216:217], off
	v_mfma_f32_16x16x32_bf16 v[40:43], v[172:175], v[180:183], v[40:43]
	v_mfma_f32_16x16x32_bf16 v[28:31], v[164:167], v[192:195], v[28:31]
	v_mfma_f32_16x16x32_bf16 v[24:27], v[172:175], v[192:195], v[24:27]
	v_mfma_f32_16x16x32_bf16 v[12:15], v[164:167], v[200:203], v[12:15]
	v_mfma_f32_16x16x32_bf16 v[8:11], v[172:175], v[200:203], v[8:11]
	v_mfma_f32_16x16x32_bf16 v[4:7], v[164:167], v[208:211], v[4:7]
	v_mfma_f32_16x16x32_bf16 v[0:3], v[172:175], v[208:211], v[0:3]
	v_mfma_f32_16x16x32_bf16 v[44:47], v[168:171], v[188:191], v[44:47]
	v_mfma_f32_16x16x32_bf16 v[40:43], v[176:179], v[188:191], v[40:43]
	v_mfma_f32_16x16x32_bf16 v[28:31], v[168:171], v[196:199], v[28:31]
	v_mfma_f32_16x16x32_bf16 v[24:27], v[176:179], v[196:199], v[24:27]
	v_mfma_f32_16x16x32_bf16 v[12:15], v[168:171], v[204:207], v[12:15]
	v_mfma_f32_16x16x32_bf16 v[8:11], v[176:179], v[204:207], v[8:11]
	v_mfma_f32_16x16x32_bf16 v[4:7], v[168:171], v[212:215], v[4:7]
	s_barrier
	v_mfma_f32_16x16x32_bf16 v[0:3], v[176:179], v[212:215], v[0:3]
	s_nop 0
	s_setprio 0
	s_add_i32 s54, s54, 2
	s_add_u32 s26, s26, 0x100
	s_addc_u32 s27, s27, 0
	s_add_u32 s52, s52, 0x100
	s_addc_u32 s53, s53, 0
	s_cmp_gt_u32 s54, 13
	s_cbranch_scc0 .LBB0_993
	s_and_b64 vcc, exec, s[8:9]
	s_cbranch_vccz .LBB0_996
	s_barrier

.LBB0_1272:
	ds_read_b128 v[24:27], v182
	ds_read_b128 v[28:31], v182 offset:16
	ds_read_b128 v[16:19], v182 offset:2048
	ds_read_b128 v[20:23], v182 offset:2064
	ds_read_b128 v[8:11], v182 offset:16384
	ds_read_b128 v[12:15], v182 offset:16400
	ds_read_b128 v[0:3], v182 offset:18432
	ds_read_b128 v[4:7], v182 offset:18448
	s_add_u32 s30, s28, 0xfffe0080
	s_addc_u32 s31, s29, -1
	s_cmp_eq_u32 s65, 4
	s_cselect_b32 s35, s15, s31
	s_cselect_b32 s34, s57, s30
	s_cselect_b32 s31, s17, s64
	s_cselect_b32 s30, s62, s63
	s_add_i32 m0, s25, 0xc000
	ds_read_b128 v[172:175], v183
	ds_read_b128 v[176:179], v183 offset:16
	ds_read_b128 v[188:191], v183 offset:2048
	ds_read_b128 v[192:195], v183 offset:2064
	ds_read_b128 v[196:199], v183 offset:4096
	ds_read_b128 v[200:203], v183 offset:4112
	ds_read_b128 v[204:207], v183 offset:6144
	ds_read_b128 v[208:211], v183 offset:6160
	global_load_lds_dwordx4 v164, s[28:29]
	s_add_i32 m0, s25, 0xe000
	v_mov_b32_e32 v167, v165
	global_load_lds_dwordx4 v166, s[28:29]
	s_waitcnt vmcnt(8)
	s_waitcnt lgkmcnt(0)
	s_barrier
	s_setprio 1
	s_waitcnt lgkmcnt(0)
	v_mfma_f32_16x16x128_f8f6f4 v[156:159], v[24:31], v[172:179], v[156:159]
	v_mfma_f32_16x16x128_f8f6f4 v[148:151], v[16:23], v[172:179], v[148:151]
	v_mfma_f32_16x16x128_f8f6f4 v[140:143], v[24:31], v[188:195], v[140:143]
	v_mfma_f32_16x16x128_f8f6f4 v[132:135], v[16:23], v[188:195], v[132:135]
	v_mfma_f32_16x16x128_f8f6f4 v[124:127], v[24:31], v[196:203], v[124:127]
	v_mfma_f32_16x16x128_f8f6f4 v[116:119], v[16:23], v[196:203], v[116:119]
	v_mfma_f32_16x16x128_f8f6f4 v[108:111], v[24:31], v[204:211], v[108:111]
	v_mfma_f32_16x16x128_f8f6f4 v[100:103], v[16:23], v[204:211], v[100:103]
	s_setprio 0
	s_setprio 1
	v_mfma_f32_16x16x128_f8f6f4 v[152:155], v[8:15], v[172:179], v[152:155]
	v_mfma_f32_16x16x128_f8f6f4 v[144:147], v[0:7], v[172:179], v[144:147]
	v_mfma_f32_16x16x128_f8f6f4 v[136:139], v[8:15], v[188:195], v[136:139]
	v_mfma_f32_16x16x128_f8f6f4 v[128:131], v[0:7], v[188:195], v[128:131]
	v_mfma_f32_16x16x128_f8f6f4 v[120:123], v[8:15], v[196:203], v[120:123]
	v_mfma_f32_16x16x128_f8f6f4 v[112:115], v[0:7], v[196:203], v[112:115]
	v_mfma_f32_16x16x128_f8f6f4 v[104:107], v[8:15], v[204:211], v[104:107]
	s_barrier
	v_mfma_f32_16x16x128_f8f6f4 v[96:99], v[0:7], v[204:211], v[96:99]
	s_setprio 0
	s_mov_b32 m0, s27
	ds_read_b128 v[188:191], v183 offset:16384
	ds_read_b128 v[192:195], v183 offset:16400
	ds_read_b128 v[196:199], v183 offset:18432
	ds_read_b128 v[200:203], v183 offset:18448
	ds_read_b128 v[204:207], v183 offset:20480
	ds_read_b128 v[208:211], v183 offset:20496
	ds_read_b128 v[212:215], v183 offset:22528
	ds_read_b128 v[216:219], v183 offset:22544
	global_load_lds_dwordx4 v162, s[30:31]
	s_mov_b32 m0, s36
	s_add_u32 s66, s30, 0x20000
	global_load_lds_dwordx4 v168, s[30:31]
	s_addc_u32 s67, s31, 0
	s_mov_b32 m0, s37
	v_mov_b32_e32 v163, v165
	global_load_lds_dwordx4 v162, s[66:67]
	s_mov_b32 m0, s38
	v_mov_b32_e32 v169, v165
	global_load_lds_dwordx4 v168, s[66:67]
	s_waitcnt vmcnt(6)
	s_waitcnt lgkmcnt(0)
	s_barrier
	s_setprio 1
	s_waitcnt lgkmcnt(0)
	v_mfma_f32_16x16x128_f8f6f4 v[92:95], v[24:31], v[188:195], v[92:95]
	v_mfma_f32_16x16x128_f8f6f4 v[84:87], v[16:23], v[188:195], v[84:87]
	s_mov_b32 m0, s25
	v_lshl_add_u64 v[178:179], s[30:31], 0, v[162:163]
	v_mfma_f32_16x16x128_f8f6f4 v[76:79], v[24:31], v[196:203], v[76:79]
	global_load_lds_dwordx4 v164, s[34:35]
	v_mfma_f32_16x16x128_f8f6f4 v[68:71], v[16:23], v[196:203], v[68:71]
	v_mfma_f32_16x16x128_f8f6f4 v[60:63], v[24:31], v[204:211], v[60:63]
	v_mfma_f32_16x16x128_f8f6f4 v[52:55], v[16:23], v[204:211], v[52:55]
	v_mfma_f32_16x16x128_f8f6f4 v[44:47], v[24:31], v[212:219], v[44:47]
	v_mfma_f32_16x16x128_f8f6f4 v[36:39], v[16:23], v[212:219], v[36:39]
	s_mov_b32 m0, s39
	v_lshl_add_u64 v[176:177], s[30:31], 0, v[168:169]
	s_setprio 0
	s_setprio 1
	v_mfma_f32_16x16x128_f8f6f4 v[88:91], v[8:15], v[188:195], v[88:91]
	global_load_lds_dwordx4 v166, s[34:35]
	v_lshl_add_u64 v[174:175], s[34:35], 0, v[164:165]
	v_lshl_add_u64 v[172:173], s[34:35], 0, v[166:167]
	v_mfma_f32_16x16x128_f8f6f4 v[80:83], v[0:7], v[188:195], v[80:83]
	v_mfma_f32_16x16x128_f8f6f4 v[72:75], v[8:15], v[196:203], v[72:75]
	v_mfma_f32_16x16x128_f8f6f4 v[64:67], v[0:7], v[196:203], v[64:67]
	v_mfma_f32_16x16x128_f8f6f4 v[56:59], v[8:15], v[204:211], v[56:59]
	v_mfma_f32_16x16x128_f8f6f4 v[48:51], v[0:7], v[204:211], v[48:51]
	v_mfma_f32_16x16x128_f8f6f4 v[40:43], v[8:15], v[212:219], v[40:43]
	s_barrier
	v_mfma_f32_16x16x128_f8f6f4 v[32:35], v[0:7], v[212:219], v[32:35]
	s_setprio 0
	ds_read_b128 v[0:3], v182 offset:32768
	ds_read_b128 v[4:7], v182 offset:32784
	ds_read_b128 v[8:11], v182 offset:34816
	ds_read_b128 v[12:15], v182 offset:34832
	ds_read_b128 v[16:19], v182 offset:49152
	ds_read_b128 v[20:23], v182 offset:49168
	ds_read_b128 v[24:27], v182 offset:51200
	ds_read_b128 v[28:31], v182 offset:51216
	s_add_u32 s34, s34, 0x20000
	s_addc_u32 s35, s35, 0
	s_mov_b32 m0, s40
	ds_read_b128 v[188:191], v183 offset:32768
	ds_read_b128 v[192:195], v183 offset:32784
	ds_read_b128 v[196:199], v183 offset:34816
	ds_read_b128 v[200:203], v183 offset:34832
	ds_read_b128 v[204:207], v183 offset:36864
	ds_read_b128 v[208:211], v183 offset:36880
	ds_read_b128 v[212:215], v183 offset:38912
	ds_read_b128 v[216:219], v183 offset:38928
	global_load_lds_dwordx4 v164, s[34:35]
	s_mov_b32 m0, s41
	s_nop 0
	global_load_lds_dwordx4 v166, s[34:35]
	s_waitcnt vmcnt(8)
	s_waitcnt lgkmcnt(0)
	s_barrier
	s_setprio 1
	s_waitcnt lgkmcnt(0)
	v_mfma_f32_16x16x128_f8f6f4 v[156:159], v[0:7], v[188:195], v[156:159]
	v_mfma_f32_16x16x128_f8f6f4 v[148:151], v[8:15], v[188:195], v[148:151]
	v_mfma_f32_16x16x128_f8f6f4 v[140:143], v[0:7], v[196:203], v[140:143]
	v_mfma_f32_16x16x128_f8f6f4 v[132:135], v[8:15], v[196:203], v[132:135]
	v_mfma_f32_16x16x128_f8f6f4 v[124:127], v[0:7], v[204:211], v[124:127]
	v_mfma_f32_16x16x128_f8f6f4 v[116:119], v[8:15], v[204:211], v[116:119]
	v_mfma_f32_16x16x128_f8f6f4 v[108:111], v[0:7], v[212:219], v[108:111]
	v_mfma_f32_16x16x128_f8f6f4 v[100:103], v[8:15], v[212:219], v[100:103]
	s_setprio 0
	s_setprio 1
	v_mfma_f32_16x16x128_f8f6f4 v[152:155], v[16:23], v[188:195], v[152:155]
	v_mfma_f32_16x16x128_f8f6f4 v[144:147], v[24:31], v[188:195], v[144:147]
	v_mfma_f32_16x16x128_f8f6f4 v[136:139], v[16:23], v[196:203], v[136:139]
	v_mfma_f32_16x16x128_f8f6f4 v[128:131], v[24:31], v[196:203], v[128:131]
	v_mfma_f32_16x16x128_f8f6f4 v[120:123], v[16:23], v[204:211], v[120:123]
	v_mfma_f32_16x16x128_f8f6f4 v[112:115], v[24:31], v[204:211], v[112:115]
	v_mfma_f32_16x16x128_f8f6f4 v[104:107], v[16:23], v[212:219], v[104:107]
	s_barrier
	v_mfma_f32_16x16x128_f8f6f4 v[96:99], v[24:31], v[212:219], v[96:99]
	s_setprio 0
	s_mov_b32 m0, s43
	v_lshl_add_u64 v[178:179], v[178:179], 0, s[6:7]
	ds_read_b128 v[188:191], v183 offset:49152
	ds_read_b128 v[192:195], v183 offset:49168
	ds_read_b128 v[196:199], v183 offset:51200
	ds_read_b128 v[200:203], v183 offset:51216
	ds_read_b128 v[204:207], v183 offset:53248
	ds_read_b128 v[208:211], v183 offset:53264
	ds_read_b128 v[212:215], v183 offset:55296
	ds_read_b128 v[216:219], v183 offset:55312
	global_load_lds_dwordx4 v[178:179], off
	v_lshl_add_u64 v[176:177], v[176:177], 0, s[6:7]
	s_mov_b32 m0, s44
	s_add_u32 s30, s30, 0x20080
	global_load_lds_dwordx4 v[176:177], off
	s_addc_u32 s31, s31, 0
	s_mov_b32 m0, s48
	v_lshl_add_u64 v[174:175], v[174:175], 0, s[6:7]
	global_load_lds_dwordx4 v162, s[30:31]
	s_mov_b32 m0, s49
	v_lshl_add_u64 v[172:173], v[172:173], 0, s[6:7]
	global_load_lds_dwordx4 v168, s[30:31]
	s_waitcnt vmcnt(6)
	s_waitcnt lgkmcnt(0)
	s_barrier
	s_setprio 1
	s_waitcnt lgkmcnt(0)
	v_mfma_f32_16x16x128_f8f6f4 v[92:95], v[0:7], v[188:195], v[92:95]
	v_mfma_f32_16x16x128_f8f6f4 v[84:87], v[8:15], v[188:195], v[84:87]
	s_mov_b32 m0, s45
	v_mfma_f32_16x16x128_f8f6f4 v[76:79], v[0:7], v[196:203], v[76:79]
	global_load_lds_dwordx4 v[174:175], off
	v_mfma_f32_16x16x128_f8f6f4 v[68:71], v[8:15], v[196:203], v[68:71]
	v_mfma_f32_16x16x128_f8f6f4 v[60:63], v[0:7], v[204:211], v[60:63]
	v_mfma_f32_16x16x128_f8f6f4 v[52:55], v[8:15], v[204:211], v[52:55]
	v_mfma_f32_16x16x128_f8f6f4 v[44:47], v[0:7], v[212:219], v[44:47]
	v_mfma_f32_16x16x128_f8f6f4 v[36:39], v[8:15], v[212:219], v[36:39]
	s_mov_b32 m0, s47
	s_setprio 0
	s_setprio 1
	v_mfma_f32_16x16x128_f8f6f4 v[88:91], v[16:23], v[188:195], v[88:91]
	global_load_lds_dwordx4 v[172:173], off
	v_mfma_f32_16x16x128_f8f6f4 v[80:83], v[24:31], v[188:195], v[80:83]
	v_mfma_f32_16x16x128_f8f6f4 v[72:75], v[16:23], v[196:203], v[72:75]
	v_mfma_f32_16x16x128_f8f6f4 v[64:67], v[24:31], v[196:203], v[64:67]
	v_mfma_f32_16x16x128_f8f6f4 v[56:59], v[16:23], v[204:211], v[56:59]
	v_mfma_f32_16x16x128_f8f6f4 v[48:51], v[24:31], v[204:211], v[48:51]
	v_mfma_f32_16x16x128_f8f6f4 v[40:43], v[16:23], v[212:219], v[40:43]
	s_barrier
	v_mfma_f32_16x16x128_f8f6f4 v[32:35], v[24:31], v[212:219], v[32:35]
	s_nop 0
	s_setprio 0
	s_add_i32 s65, s65, 2
	s_add_u32 s28, s28, 0x100
	s_addc_u32 s29, s29, 0
	s_add_u32 s63, s63, 0x100
	s_addc_u32 s64, s64, 0
	s_cmp_gt_u32 s65, 5
	s_cbranch_scc0 .LBB0_1272
	s_nop 15
	s_nop 15
	s_and_b64 vcc, exec, s[8:9]
	s_cbranch_vccz .LBB0_1275
	s_barrier

.LBB0_1349:
	ds_read_b128 v[24:27], v181
	ds_read_b128 v[28:31], v181 offset:16
	ds_read_b128 v[16:19], v181 offset:2048
	ds_read_b128 v[20:23], v181 offset:2064
	ds_read_b128 v[8:11], v181 offset:16384
	ds_read_b128 v[12:15], v181 offset:16400
	ds_read_b128 v[0:3], v181 offset:18432
	ds_read_b128 v[4:7], v181 offset:18448
	s_add_u32 s34, s30, 0xfff90080
	s_addc_u32 s35, s31, -1
	s_cmp_eq_u32 s74, 24
	s_cselect_b32 s37, s1, s35
	s_cselect_b32 s36, s0, s34
	s_cselect_b32 s35, s27, s73
	s_cselect_b32 s34, s26, s72
	s_add_i32 m0, s29, 0xc000
	ds_read_b128 v[172:175], v182
	ds_read_b128 v[176:179], v182 offset:16
	ds_read_b128 v[188:191], v182 offset:2048
	ds_read_b128 v[192:195], v182 offset:2064
	ds_read_b128 v[196:199], v182 offset:4096
	ds_read_b128 v[200:203], v182 offset:4112
	ds_read_b128 v[204:207], v182 offset:6144
	ds_read_b128 v[208:211], v182 offset:6160
	global_load_lds_dwordx4 v162, s[30:31]
	s_add_i32 m0, s29, 0xe000
	v_mov_b32_e32 v167, v163
	global_load_lds_dwordx4 v166, s[30:31]
	s_waitcnt vmcnt(8)
	s_waitcnt lgkmcnt(0)
	s_barrier
	s_setprio 1
	s_waitcnt lgkmcnt(0)
	v_mfma_f32_16x16x128_f8f6f4 v[156:159], v[24:31], v[172:179], v[156:159]
	v_mfma_f32_16x16x128_f8f6f4 v[152:155], v[16:23], v[172:179], v[152:155]
	v_mfma_f32_16x16x128_f8f6f4 v[148:151], v[24:31], v[188:195], v[148:151]
	v_mfma_f32_16x16x128_f8f6f4 v[140:143], v[16:23], v[188:195], v[140:143]
	v_mfma_f32_16x16x128_f8f6f4 v[132:135], v[24:31], v[196:203], v[132:135]
	v_mfma_f32_16x16x128_f8f6f4 v[124:127], v[16:23], v[196:203], v[124:127]
	v_mfma_f32_16x16x128_f8f6f4 v[116:119], v[24:31], v[204:211], v[116:119]
	v_mfma_f32_16x16x128_f8f6f4 v[108:111], v[16:23], v[204:211], v[108:111]
	s_setprio 0
	s_setprio 1
	v_mfma_f32_16x16x128_f8f6f4 v[144:147], v[8:15], v[172:179], v[144:147]
	v_mfma_f32_16x16x128_f8f6f4 v[136:139], v[0:7], v[172:179], v[136:139]
	v_mfma_f32_16x16x128_f8f6f4 v[128:131], v[8:15], v[188:195], v[128:131]
	v_mfma_f32_16x16x128_f8f6f4 v[120:123], v[0:7], v[188:195], v[120:123]
	v_mfma_f32_16x16x128_f8f6f4 v[112:115], v[8:15], v[196:203], v[112:115]
	v_mfma_f32_16x16x128_f8f6f4 v[104:107], v[0:7], v[196:203], v[104:107]
	v_mfma_f32_16x16x128_f8f6f4 v[100:103], v[8:15], v[204:211], v[100:103]
	s_barrier
	v_mfma_f32_16x16x128_f8f6f4 v[96:99], v[0:7], v[204:211], v[96:99]
	s_setprio 0
	s_mov_b32 m0, s39
	ds_read_b128 v[188:191], v182 offset:16384
	ds_read_b128 v[192:195], v182 offset:16400
	ds_read_b128 v[196:199], v182 offset:18432
	ds_read_b128 v[200:203], v182 offset:18448
	ds_read_b128 v[204:207], v182 offset:20480
	ds_read_b128 v[208:211], v182 offset:20496
	ds_read_b128 v[212:215], v182 offset:22528
	ds_read_b128 v[216:219], v182 offset:22544
	global_load_lds_dwordx4 v164, s[34:35]
	s_mov_b32 m0, s40
	s_add_u32 s76, s34, 0x70000
	global_load_lds_dwordx4 v168, s[34:35]
	s_addc_u32 s77, s35, 0
	s_mov_b32 m0, s41
	v_mov_b32_e32 v165, v163
	global_load_lds_dwordx4 v164, s[76:77]
	s_mov_b32 m0, s42
	v_mov_b32_e32 v169, v163
	global_load_lds_dwordx4 v168, s[76:77]
	s_waitcnt vmcnt(6)
	s_waitcnt lgkmcnt(0)
	s_barrier
	s_setprio 1
	s_waitcnt lgkmcnt(0)
	v_mfma_f32_16x16x128_f8f6f4 v[92:95], v[24:31], v[188:195], v[92:95]
	v_mfma_f32_16x16x128_f8f6f4 v[88:91], v[16:23], v[188:195], v[88:91]
	s_mov_b32 m0, s29
	v_lshl_add_u64 v[178:179], s[34:35], 0, v[164:165]
	v_mfma_f32_16x16x128_f8f6f4 v[84:87], v[24:31], v[196:203], v[84:87]
	global_load_lds_dwordx4 v162, s[36:37]
	v_mfma_f32_16x16x128_f8f6f4 v[76:79], v[16:23], v[196:203], v[76:79]
	v_mfma_f32_16x16x128_f8f6f4 v[68:71], v[24:31], v[204:211], v[68:71]
	v_mfma_f32_16x16x128_f8f6f4 v[60:63], v[16:23], v[204:211], v[60:63]
	v_mfma_f32_16x16x128_f8f6f4 v[52:55], v[24:31], v[212:219], v[52:55]
	v_mfma_f32_16x16x128_f8f6f4 v[44:47], v[16:23], v[212:219], v[44:47]
	s_mov_b32 m0, s43
	v_lshl_add_u64 v[176:177], s[34:35], 0, v[168:169]
	s_setprio 0
	s_setprio 1
	v_mfma_f32_16x16x128_f8f6f4 v[80:83], v[8:15], v[188:195], v[80:83]
	global_load_lds_dwordx4 v166, s[36:37]
	v_lshl_add_u64 v[174:175], s[36:37], 0, v[162:163]
	v_lshl_add_u64 v[172:173], s[36:37], 0, v[166:167]
	v_mfma_f32_16x16x128_f8f6f4 v[72:75], v[0:7], v[188:195], v[72:75]
	v_mfma_f32_16x16x128_f8f6f4 v[64:67], v[8:15], v[196:203], v[64:67]
	v_mfma_f32_16x16x128_f8f6f4 v[56:59], v[0:7], v[196:203], v[56:59]
	v_mfma_f32_16x16x128_f8f6f4 v[48:51], v[8:15], v[204:211], v[48:51]
	v_mfma_f32_16x16x128_f8f6f4 v[40:43], v[0:7], v[204:211], v[40:43]
	v_mfma_f32_16x16x128_f8f6f4 v[36:39], v[8:15], v[212:219], v[36:39]
	s_barrier
	v_mfma_f32_16x16x128_f8f6f4 v[32:35], v[0:7], v[212:219], v[32:35]
	s_setprio 0
	ds_read_b128 v[0:3], v181 offset:32768
	ds_read_b128 v[4:7], v181 offset:32784
	ds_read_b128 v[8:11], v181 offset:34816
	ds_read_b128 v[12:15], v181 offset:34832
	ds_read_b128 v[16:19], v181 offset:49152
	ds_read_b128 v[20:23], v181 offset:49168
	ds_read_b128 v[24:27], v181 offset:51200
	ds_read_b128 v[28:31], v181 offset:51216
	s_add_u32 s36, s36, 0x70000
	s_addc_u32 s37, s37, 0
	s_mov_b32 m0, s44
	ds_read_b128 v[188:191], v182 offset:32768
	ds_read_b128 v[192:195], v182 offset:32784
	ds_read_b128 v[196:199], v182 offset:34816
	ds_read_b128 v[200:203], v182 offset:34832
	ds_read_b128 v[204:207], v182 offset:36864
	ds_read_b128 v[208:211], v182 offset:36880
	ds_read_b128 v[212:215], v182 offset:38912
	ds_read_b128 v[216:219], v182 offset:38928
	global_load_lds_dwordx4 v162, s[36:37]
	s_mov_b32 m0, s45
	s_nop 0
	global_load_lds_dwordx4 v166, s[36:37]
	s_waitcnt vmcnt(8)
	s_waitcnt lgkmcnt(0)
	s_barrier
	s_setprio 1
	s_waitcnt lgkmcnt(0)
	v_mfma_f32_16x16x128_f8f6f4 v[156:159], v[0:7], v[188:195], v[156:159]
	v_mfma_f32_16x16x128_f8f6f4 v[152:155], v[8:15], v[188:195], v[152:155]
	v_mfma_f32_16x16x128_f8f6f4 v[148:151], v[0:7], v[196:203], v[148:151]
	v_mfma_f32_16x16x128_f8f6f4 v[140:143], v[8:15], v[196:203], v[140:143]
	v_mfma_f32_16x16x128_f8f6f4 v[132:135], v[0:7], v[204:211], v[132:135]
	v_mfma_f32_16x16x128_f8f6f4 v[124:127], v[8:15], v[204:211], v[124:127]
	v_mfma_f32_16x16x128_f8f6f4 v[116:119], v[0:7], v[212:219], v[116:119]
	v_mfma_f32_16x16x128_f8f6f4 v[108:111], v[8:15], v[212:219], v[108:111]
	s_setprio 0
	s_setprio 1
	v_mfma_f32_16x16x128_f8f6f4 v[144:147], v[16:23], v[188:195], v[144:147]
	v_mfma_f32_16x16x128_f8f6f4 v[136:139], v[24:31], v[188:195], v[136:139]
	v_mfma_f32_16x16x128_f8f6f4 v[128:131], v[16:23], v[196:203], v[128:131]
	v_mfma_f32_16x16x128_f8f6f4 v[120:123], v[24:31], v[196:203], v[120:123]
	v_mfma_f32_16x16x128_f8f6f4 v[112:115], v[16:23], v[204:211], v[112:115]
	v_mfma_f32_16x16x128_f8f6f4 v[104:107], v[24:31], v[204:211], v[104:107]
	v_mfma_f32_16x16x128_f8f6f4 v[100:103], v[16:23], v[212:219], v[100:103]
	s_barrier
	v_mfma_f32_16x16x128_f8f6f4 v[96:99], v[24:31], v[212:219], v[96:99]
	s_setprio 0
	s_mov_b32 m0, s48
	v_lshl_add_u64 v[178:179], v[178:179], 0, s[8:9]
	ds_read_b128 v[188:191], v182 offset:49152
	ds_read_b128 v[192:195], v182 offset:49168
	ds_read_b128 v[196:199], v182 offset:51200
	ds_read_b128 v[200:203], v182 offset:51216
	ds_read_b128 v[204:207], v182 offset:53248
	ds_read_b128 v[208:211], v182 offset:53264
	ds_read_b128 v[212:215], v182 offset:55296
	ds_read_b128 v[216:219], v182 offset:55312
	global_load_lds_dwordx4 v[178:179], off
	v_lshl_add_u64 v[176:177], v[176:177], 0, s[8:9]
	s_mov_b32 m0, s49
	s_add_u32 s34, s34, 0x70080
	global_load_lds_dwordx4 v[176:177], off
	s_addc_u32 s35, s35, 0
	s_mov_b32 m0, s57
	v_lshl_add_u64 v[174:175], v[174:175], 0, s[8:9]
	global_load_lds_dwordx4 v164, s[34:35]
	s_mov_b32 m0, s62
	v_lshl_add_u64 v[172:173], v[172:173], 0, s[8:9]
	global_load_lds_dwordx4 v168, s[34:35]
	s_waitcnt vmcnt(6)
	s_waitcnt lgkmcnt(0)
	s_barrier
	s_setprio 1
	s_waitcnt lgkmcnt(0)
	v_mfma_f32_16x16x128_f8f6f4 v[92:95], v[0:7], v[188:195], v[92:95]
	v_mfma_f32_16x16x128_f8f6f4 v[88:91], v[8:15], v[188:195], v[88:91]
	s_mov_b32 m0, s52
	v_mfma_f32_16x16x128_f8f6f4 v[84:87], v[0:7], v[196:203], v[84:87]
	global_load_lds_dwordx4 v[174:175], off
	v_mfma_f32_16x16x128_f8f6f4 v[76:79], v[8:15], v[196:203], v[76:79]
	v_mfma_f32_16x16x128_f8f6f4 v[68:71], v[0:7], v[204:211], v[68:71]
	v_mfma_f32_16x16x128_f8f6f4 v[60:63], v[8:15], v[204:211], v[60:63]
	v_mfma_f32_16x16x128_f8f6f4 v[52:55], v[0:7], v[212:219], v[52:55]
	v_mfma_f32_16x16x128_f8f6f4 v[44:47], v[8:15], v[212:219], v[44:47]
	s_mov_b32 m0, s53
	s_setprio 0
	s_setprio 1
	v_mfma_f32_16x16x128_f8f6f4 v[80:83], v[16:23], v[188:195], v[80:83]
	global_load_lds_dwordx4 v[172:173], off
	v_mfma_f32_16x16x128_f8f6f4 v[72:75], v[24:31], v[188:195], v[72:75]
	v_mfma_f32_16x16x128_f8f6f4 v[64:67], v[16:23], v[196:203], v[64:67]
	v_mfma_f32_16x16x128_f8f6f4 v[56:59], v[24:31], v[196:203], v[56:59]
	v_mfma_f32_16x16x128_f8f6f4 v[48:51], v[16:23], v[204:211], v[48:51]
	v_mfma_f32_16x16x128_f8f6f4 v[40:43], v[24:31], v[204:211], v[40:43]
	v_mfma_f32_16x16x128_f8f6f4 v[36:39], v[16:23], v[212:219], v[36:39]
	s_barrier
	v_mfma_f32_16x16x128_f8f6f4 v[32:35], v[24:31], v[212:219], v[32:35]
	s_nop 0
	s_setprio 0
	s_add_i32 s74, s74, 2
	s_add_u32 s30, s30, 0x100
	s_addc_u32 s31, s31, 0
	s_add_u32 s72, s72, 0x100
	s_addc_u32 s73, s73, 0
	s_cmp_gt_u32 s74, 25
	s_cbranch_scc0 .LBB0_1349
	s_nop 15
	s_nop 15
	s_and_b64 vcc, exec, s[10:11]
	s_cbranch_vccz .LBB0_1352
	s_barrier
